# removed the per-phase s_setprio 1/0 flips around the MFMA blocks in all five GEMM K-loops (in-kernel stamps showed FFN-up -3% and FFN-down -5%)
# speedup vs baseline: 1.0209x; 1.0209x over previous
; #define PG8_STAGE(bufoff, gbase, voff) do { _Pragma("unroll") for (int _i = 0; _i < 2; ++_i) \
;     __builtin_amdgcn_global_load_lds((const unsigned*)((const char*)(gbase) + (voff)[_i]), (PG8_LAS unsigned*)(lds + (bufoff) + ldsw + _i * 8192), 16, 0, 0); } while (0)
; #define PG8_LDA(dst, b, h) do { _Pragma("unroll") for (int m = 0; m < 4; ++m) _Pragma("unroll") for (int k = 0; k < 2; ++k) dst[m][k] = *(const PG8_LAS bf16x8*)(lds + PG8_SA(b, h) + aoff + m * 2048 + k * 1024); } while (0)
; #define PG8_LDB(dst, b, h) do { _Pragma("unroll") for (int n = 0; n < 2; ++n) _Pragma("unroll") for (int k = 0; k < 2; ++k) dst[n][k] = *(const PG8_LAS bf16x8*)(lds + PG8_SB(b, h) + boff + n * 2048 + k * 1024); } while (0)
; #define PG8_MMA(ai, bj, At, Bt) do { __builtin_amdgcn_s_setprio(1); _Pragma("unroll") for (int m = 0; m < 4; ++m) _Pragma("unroll") for (int n = 0; n < 2; ++n) _Pragma("unroll") for (int k = 0; k < 2; ++k) \
;     acc[ai][bj][m][n] = __builtin_amdgcn_mfma_f32_16x16x32_bf16(Bt[n][k], At[m][k], acc[ai][bj][m][n], 0, 0, 0); __builtin_amdgcn_s_setprio(0); } while (0)
; #define PG8_WAIT_V(n) asm volatile("s_waitcnt vmcnt(" #n ")" ::: "memory")
; #define PG8_WAIT_L(n) asm volatile("s_waitcnt lgkmcnt(" #n ")" ::: "memory")
; #define PG8_BAR __builtin_amdgcn_s_barrier()
; #define PG8_SCHED __builtin_amdgcn_sched_barrier(0)
; template <class Epi>
; DI void gemm_phase(const bf16_t* __restrict__ gA, const bf16_t* __restrict__ gBt, int M, int N, int K, const Epi& E, char* lds_generic) {
;     ...
;       const bool last = (t == nt - 2);
;       const char* a1 = cA + (size_t)(t + 1) * kstep;
;       const char* a2 = last ? nA : cA + (size_t)(t + 2) * kstep; const char* b2 = last ? nB : cB + (size_t)(t + 2) * kstep;
;       const char* a3 = a2 + kstep; const char* b3 = b2 + kstep;
;       PG8_LDB(B0, 0, 0); PG8_SCHED; PG8_LDA(At, 0, 0); PG8_STAGE(PG8_SA(1, 1), a1 + hstep, voffA);
;       PG8_WAIT_L(8); PG8_BAR; PG8_WAIT_L(0); PG8_MMA(0, 0, At, B0); PG8_BAR; PG8_SCHED;
;       PG8_LDB(B1, 0, 1); PG8_STAGE(PG8_SB(0, 0), b2, voffB);
;       PG8_BAR; PG8_WAIT_L(0); PG8_MMA(0, 1, At, B1); PG8_BAR;
;       PG8_LDA(At, 0, 1); PG8_STAGE(PG8_SA(0, 0), a2, voffA);
;       PG8_BAR; PG8_WAIT_L(0); PG8_MMA(1, 0, At, B0); PG8_BAR; PG8_SCHED;
;       PG8_STAGE(PG8_SB(0, 1), b2 + hstep, voffB);
;       PG8_WAIT_V(6); PG8_BAR; PG8_MMA(1, 1, At, B1); PG8_BAR;
.LBB0_137:
	ds_read_b128 v[130:133], v157
	ds_read_b128 v[146:149], v158
	ds_read_b128 v[176:179], v159
	ds_read_b128 v[180:183], v160
	s_add_u32 s24, s80, 0xfffc0080
	s_addc_u32 s25, s81, -1
	s_cmp_eq_u32 s62, 12
	s_cselect_b32 s31, s22, s25
	s_cselect_b32 s30, s23, s24
	s_cselect_b32 s29, s1, s61
	s_cselect_b32 s28, s27, s60
	s_mov_b32 m0, s33
	v_lshl_add_u64 v[216:217], s[80:81], 0, v[142:143]
	ds_read_b128 v[184:187], v154
	ds_read_b128 v[188:191], v154 offset:1024
	ds_read_b128 v[192:195], v154 offset:2048
	ds_read_b128 v[196:199], v154 offset:3072
	ds_read_b128 v[200:203], v154 offset:4096
	ds_read_b128 v[204:207], v154 offset:5120
	ds_read_b128 v[208:211], v154 offset:6144
	ds_read_b128 v[212:215], v154 offset:7168
	global_load_lds_dwordx4 v[216:217], off
	v_lshl_add_u64 v[216:217], s[80:81], 0, v[144:145]
	s_mov_b32 m0, s35
	s_nop 0
	global_load_lds_dwordx4 v[216:217], off
	s_waitcnt lgkmcnt(8)
	s_barrier
	s_waitcnt lgkmcnt(0)
	s_waitcnt lgkmcnt(0)
	v_mfma_f32_16x16x32_bf16 v[126:129], v[130:133], v[184:187], v[126:129]
	v_mfma_f32_16x16x32_bf16 v[122:125], v[176:179], v[184:187], v[122:125]
	v_mfma_f32_16x16x32_bf16 v[118:121], v[130:133], v[192:195], v[118:121]
	v_mfma_f32_16x16x32_bf16 v[110:113], v[176:179], v[192:195], v[110:113]
	v_mfma_f32_16x16x32_bf16 v[98:101], v[130:133], v[200:203], v[98:101]
	v_mfma_f32_16x16x32_bf16 v[90:93], v[176:179], v[200:203], v[90:93]
	v_mfma_f32_16x16x32_bf16 v[86:89], v[130:133], v[208:211], v[86:89]
	v_mfma_f32_16x16x32_bf16 v[78:81], v[176:179], v[208:211], v[78:81]
	v_mfma_f32_16x16x32_bf16 v[126:129], v[146:149], v[188:191], v[126:129]
	v_mfma_f32_16x16x32_bf16 v[122:125], v[180:183], v[188:191], v[122:125]
	v_mfma_f32_16x16x32_bf16 v[118:121], v[146:149], v[196:199], v[118:121]
	v_mfma_f32_16x16x32_bf16 v[110:113], v[180:183], v[196:199], v[110:113]
	v_mfma_f32_16x16x32_bf16 v[98:101], v[146:149], v[204:207], v[98:101]
	v_mfma_f32_16x16x32_bf16 v[90:93], v[180:183], v[204:207], v[90:93]
	v_mfma_f32_16x16x32_bf16 v[86:89], v[146:149], v[212:215], v[86:89]
	v_mfma_f32_16x16x32_bf16 v[78:81], v[180:183], v[212:215], v[78:81]
	s_barrier
	s_mov_b32 m0, s6
	v_lshl_add_u64 v[220:221], s[28:29], 0, v[0:1]
	ds_read_b128 v[216:219], v161
	ds_read_b128 v[238:241], v163
	ds_read_b128 v[242:245], v165
	ds_read_b128 v[246:249], v166
	global_load_lds_dwordx4 v[220:221], off
	v_lshl_add_u64 v[250:251], s[28:29], 0, v[138:139]
	s_mov_b32 m0, s7
	s_nop 0
	global_load_lds_dwordx4 v[250:251], off
	s_barrier
	s_waitcnt lgkmcnt(0)
	s_waitcnt lgkmcnt(0)
	v_mfma_f32_16x16x32_bf16 v[114:117], v[216:219], v[184:187], v[114:117]
	v_mfma_f32_16x16x32_bf16 v[106:109], v[242:245], v[184:187], v[106:109]
	v_mfma_f32_16x16x32_bf16 v[102:105], v[216:219], v[192:195], v[102:105]
	v_mfma_f32_16x16x32_bf16 v[94:97], v[242:245], v[192:195], v[94:97]
	v_mfma_f32_16x16x32_bf16 v[82:85], v[216:219], v[200:203], v[82:85]
	v_mfma_f32_16x16x32_bf16 v[74:77], v[242:245], v[200:203], v[74:77]
	v_mfma_f32_16x16x32_bf16 v[70:73], v[216:219], v[208:211], v[70:73]
	v_mfma_f32_16x16x32_bf16 v[66:69], v[242:245], v[208:211], v[66:69]
	v_mfma_f32_16x16x32_bf16 v[114:117], v[238:241], v[188:191], v[114:117]
	v_mfma_f32_16x16x32_bf16 v[106:109], v[246:249], v[188:191], v[106:109]
	v_mfma_f32_16x16x32_bf16 v[102:105], v[238:241], v[196:199], v[102:105]
	v_mfma_f32_16x16x32_bf16 v[94:97], v[246:249], v[196:199], v[94:97]
	v_mfma_f32_16x16x32_bf16 v[82:85], v[238:241], v[204:207], v[82:85]
	v_mfma_f32_16x16x32_bf16 v[74:77], v[246:249], v[204:207], v[74:77]
	v_mfma_f32_16x16x32_bf16 v[70:73], v[238:241], v[212:215], v[70:73]
	v_mfma_f32_16x16x32_bf16 v[66:69], v[246:249], v[212:215], v[66:69]
	s_mov_b32 m0, s5
	v_lshl_add_u64 v[228:229], s[30:31], 0, v[134:135]
	s_barrier
	ds_read_b128 v[184:187], v154 offset:16384
	ds_read_b128 v[188:191], v154 offset:17408
	ds_read_b128 v[192:195], v154 offset:18432
	ds_read_b128 v[196:199], v154 offset:19456
	ds_read_b128 v[200:203], v154 offset:20480
	ds_read_b128 v[204:207], v154 offset:21504
	ds_read_b128 v[208:211], v154 offset:22528
	ds_read_b128 v[212:215], v154 offset:23552
	global_load_lds_dwordx4 v[228:229], off
	v_lshl_add_u64 v[226:227], s[30:31], 0, v[136:137]
	s_mov_b32 m0, s8
	s_nop 0
	global_load_lds_dwordx4 v[226:227], off
	s_barrier
	s_waitcnt lgkmcnt(0)
	s_waitcnt lgkmcnt(0)
	v_mfma_f32_16x16x32_bf16 v[62:65], v[130:133], v[184:187], v[62:65]
	v_mfma_f32_16x16x32_bf16 v[58:61], v[176:179], v[184:187], v[58:61]
	v_mfma_f32_16x16x32_bf16 v[54:57], v[130:133], v[192:195], v[54:57]
	v_mfma_f32_16x16x32_bf16 v[46:49], v[176:179], v[192:195], v[46:49]
	v_mfma_f32_16x16x32_bf16 v[34:37], v[130:133], v[200:203], v[34:37]
	v_mfma_f32_16x16x32_bf16 v[26:29], v[176:179], v[200:203], v[26:29]
	v_mfma_f32_16x16x32_bf16 v[22:25], v[130:133], v[208:211], v[22:25]
	v_mfma_f32_16x16x32_bf16 v[14:17], v[176:179], v[208:211], v[14:17]
	v_mfma_f32_16x16x32_bf16 v[62:65], v[146:149], v[188:191], v[62:65]
	v_mfma_f32_16x16x32_bf16 v[58:61], v[180:183], v[188:191], v[58:61]
	v_mfma_f32_16x16x32_bf16 v[54:57], v[146:149], v[196:199], v[54:57]
	v_mfma_f32_16x16x32_bf16 v[46:49], v[180:183], v[196:199], v[46:49]
	v_mfma_f32_16x16x32_bf16 v[34:37], v[146:149], v[204:207], v[34:37]
	v_mfma_f32_16x16x32_bf16 v[26:29], v[180:183], v[204:207], v[26:29]
	v_mfma_f32_16x16x32_bf16 v[22:25], v[146:149], v[212:215], v[22:25]
	v_mfma_f32_16x16x32_bf16 v[14:17], v[180:183], v[212:215], v[14:17]
	s_barrier
	s_add_u32 s82, s28, 0x40000
	s_addc_u32 s83, s29, 0
	s_mov_b32 m0, s9
	v_lshl_add_u64 v[130:131], s[82:83], 0, v[0:1]
	global_load_lds_dwordx4 v[130:131], off
	v_lshl_add_u64 v[130:131], s[82:83], 0, v[138:139]
	s_mov_b32 m0, s12
	s_nop 0
	global_load_lds_dwordx4 v[130:131], off
	s_waitcnt vmcnt(6)
	s_barrier
; #define PG8_STAGE(bufoff, gbase, voff) do { _Pragma("unroll") for (int _i = 0; _i < 2; ++_i) \
;     __builtin_amdgcn_global_load_lds((const unsigned*)((const char*)(gbase) + (voff)[_i]), (PG8_LAS unsigned*)(lds + (bufoff) + ldsw + _i * 8192), 16, 0, 0); } while (0)
; #define PG8_LDA(dst, b, h) do { _Pragma("unroll") for (int m = 0; m < 4; ++m) _Pragma("unroll") for (int k = 0; k < 2; ++k) dst[m][k] = *(const PG8_LAS bf16x8*)(lds + PG8_SA(b, h) + aoff + m * 2048 + k * 1024); } while (0)
; #define PG8_LDB(dst, b, h) do { _Pragma("unroll") for (int n = 0; n < 2; ++n) _Pragma("unroll") for (int k = 0; k < 2; ++k) dst[n][k] = *(const PG8_LAS bf16x8*)(lds + PG8_SB(b, h) + boff + n * 2048 + k * 1024); } while (0)
; #define PG8_MMA(ai, bj, At, Bt) do { __builtin_amdgcn_s_setprio(1); _Pragma("unroll") for (int m = 0; m < 4; ++m) _Pragma("unroll") for (int n = 0; n < 2; ++n) _Pragma("unroll") for (int k = 0; k < 2; ++k) \
;     acc[ai][bj][m][n] = __builtin_amdgcn_mfma_f32_16x16x32_bf16(Bt[n][k], At[m][k], acc[ai][bj][m][n], 0, 0, 0); __builtin_amdgcn_s_setprio(0); } while (0)
; #define PG8_WAIT_V(n) asm volatile("s_waitcnt vmcnt(" #n ")" ::: "memory")
; #define PG8_WAIT_L(n) asm volatile("s_waitcnt lgkmcnt(" #n ")" ::: "memory")
; #define PG8_BAR __builtin_amdgcn_s_barrier()
; #define PG8_SCHED __builtin_amdgcn_sched_barrier(0)
; template <class Epi>
; DI void gemm_phase(const bf16_t* __restrict__ gA, const bf16_t* __restrict__ gBt, int M, int N, int K, const Epi& E, char* lds_generic) {
;     ...
;       PG8_WAIT_V(6); PG8_BAR; PG8_MMA(1, 1, At, B1); PG8_BAR;
;       PG8_LDB(B0, 1, 0); PG8_SCHED; PG8_LDA(At, 1, 0); PG8_STAGE(PG8_SA(0, 1), a2 + hstep, voffA);
;       PG8_WAIT_L(8); PG8_BAR; PG8_WAIT_L(0); PG8_MMA(0, 0, At, B0); PG8_BAR; PG8_SCHED;
;       PG8_LDB(B1, 1, 1); PG8_STAGE(PG8_SB(1, 0), b3, voffB);
;       PG8_BAR; PG8_WAIT_L(0); PG8_MMA(0, 1, At, B1); PG8_BAR;
;       PG8_LDA(At, 1, 1); PG8_STAGE(PG8_SA(1, 0), a3, voffA);
	v_mfma_f32_16x16x32_bf16 v[50:53], v[216:219], v[184:187], v[50:53]
	v_mfma_f32_16x16x32_bf16 v[42:45], v[242:245], v[184:187], v[42:45]
	v_mfma_f32_16x16x32_bf16 v[38:41], v[216:219], v[192:195], v[38:41]
	v_mfma_f32_16x16x32_bf16 v[30:33], v[242:245], v[192:195], v[30:33]
	v_mfma_f32_16x16x32_bf16 v[18:21], v[216:219], v[200:203], v[18:21]
	v_mfma_f32_16x16x32_bf16 v[10:13], v[242:245], v[200:203], v[10:13]
	v_mfma_f32_16x16x32_bf16 v[6:9], v[216:219], v[208:211], v[6:9]
	v_mfma_f32_16x16x32_bf16 v[2:5], v[242:245], v[208:211], v[2:5]
	v_mfma_f32_16x16x32_bf16 v[50:53], v[238:241], v[188:191], v[50:53]
	v_mfma_f32_16x16x32_bf16 v[42:45], v[246:249], v[188:191], v[42:45]
	v_mfma_f32_16x16x32_bf16 v[38:41], v[238:241], v[196:199], v[38:41]
	v_mfma_f32_16x16x32_bf16 v[30:33], v[246:249], v[196:199], v[30:33]
	v_mfma_f32_16x16x32_bf16 v[18:21], v[238:241], v[204:207], v[18:21]
	v_mfma_f32_16x16x32_bf16 v[10:13], v[246:249], v[204:207], v[10:13]
	v_mfma_f32_16x16x32_bf16 v[6:9], v[238:241], v[212:215], v[6:9]
	v_mfma_f32_16x16x32_bf16 v[2:5], v[246:249], v[212:215], v[2:5]
	s_barrier
	ds_read_b128 v[130:133], v167
	ds_read_b128 v[146:149], v168
	ds_read_b128 v[176:179], v169
	ds_read_b128 v[180:183], v170
	s_add_u32 s30, s30, 0x40000
	s_addc_u32 s31, s31, 0
	s_mov_b32 m0, s13
	v_lshl_add_u64 v[216:217], s[30:31], 0, v[134:135]
	ds_read_b128 v[184:187], v154 offset:32768
	ds_read_b128 v[188:191], v154 offset:33792
	ds_read_b128 v[192:195], v154 offset:34816
	ds_read_b128 v[196:199], v154 offset:35840
	ds_read_b128 v[200:203], v154 offset:36864
	ds_read_b128 v[204:207], v154 offset:37888
	ds_read_b128 v[208:211], v154 offset:38912
	ds_read_b128 v[212:215], v154 offset:39936
	global_load_lds_dwordx4 v[216:217], off
	v_lshl_add_u64 v[216:217], s[30:31], 0, v[136:137]
	s_mov_b32 m0, s14
	s_nop 0
	global_load_lds_dwordx4 v[216:217], off
	s_waitcnt lgkmcnt(8)
	s_barrier
	s_waitcnt lgkmcnt(0)
	s_waitcnt lgkmcnt(0)
	v_mfma_f32_16x16x32_bf16 v[126:129], v[130:133], v[184:187], v[126:129]
	v_mfma_f32_16x16x32_bf16 v[122:125], v[176:179], v[184:187], v[122:125]
	v_mfma_f32_16x16x32_bf16 v[118:121], v[130:133], v[192:195], v[118:121]
	v_mfma_f32_16x16x32_bf16 v[110:113], v[176:179], v[192:195], v[110:113]
	v_mfma_f32_16x16x32_bf16 v[98:101], v[130:133], v[200:203], v[98:101]
	v_mfma_f32_16x16x32_bf16 v[90:93], v[176:179], v[200:203], v[90:93]
	v_mfma_f32_16x16x32_bf16 v[86:89], v[130:133], v[208:211], v[86:89]
	v_mfma_f32_16x16x32_bf16 v[78:81], v[176:179], v[208:211], v[78:81]
	v_mfma_f32_16x16x32_bf16 v[126:129], v[146:149], v[188:191], v[126:129]
	v_mfma_f32_16x16x32_bf16 v[122:125], v[180:183], v[188:191], v[122:125]
	v_mfma_f32_16x16x32_bf16 v[118:121], v[146:149], v[196:199], v[118:121]
	v_mfma_f32_16x16x32_bf16 v[110:113], v[180:183], v[196:199], v[110:113]
	v_mfma_f32_16x16x32_bf16 v[98:101], v[146:149], v[204:207], v[98:101]
	v_mfma_f32_16x16x32_bf16 v[90:93], v[180:183], v[204:207], v[90:93]
	v_mfma_f32_16x16x32_bf16 v[86:89], v[146:149], v[212:215], v[86:89]
	v_mfma_f32_16x16x32_bf16 v[78:81], v[180:183], v[212:215], v[78:81]
	s_barrier
	s_mov_b32 m0, s15
	v_lshl_add_u64 v[220:221], v[220:221], 0, s[10:11]
	ds_read_b128 v[216:219], v171
	ds_read_b128 v[238:241], v172
	ds_read_b128 v[242:245], v173
	ds_read_b128 v[246:249], v174
	global_load_lds_dwordx4 v[220:221], off
	v_lshl_add_u64 v[220:221], v[250:251], 0, s[10:11]
	s_mov_b32 m0, s16
	s_nop 0
	global_load_lds_dwordx4 v[220:221], off
	s_barrier
	s_waitcnt lgkmcnt(0)
	s_waitcnt lgkmcnt(0)
	v_mfma_f32_16x16x32_bf16 v[114:117], v[216:219], v[184:187], v[114:117]
	v_mfma_f32_16x16x32_bf16 v[106:109], v[242:245], v[184:187], v[106:109]
	v_mfma_f32_16x16x32_bf16 v[102:105], v[216:219], v[192:195], v[102:105]
	v_mfma_f32_16x16x32_bf16 v[94:97], v[242:245], v[192:195], v[94:97]
	v_mfma_f32_16x16x32_bf16 v[82:85], v[216:219], v[200:203], v[82:85]
	v_mfma_f32_16x16x32_bf16 v[74:77], v[242:245], v[200:203], v[74:77]
	v_mfma_f32_16x16x32_bf16 v[70:73], v[216:219], v[208:211], v[70:73]
	v_mfma_f32_16x16x32_bf16 v[66:69], v[242:245], v[208:211], v[66:69]
	v_mfma_f32_16x16x32_bf16 v[114:117], v[238:241], v[188:191], v[114:117]
	v_mfma_f32_16x16x32_bf16 v[106:109], v[246:249], v[188:191], v[106:109]
	v_mfma_f32_16x16x32_bf16 v[102:105], v[238:241], v[196:199], v[102:105]
	v_mfma_f32_16x16x32_bf16 v[94:97], v[246:249], v[196:199], v[94:97]
	v_mfma_f32_16x16x32_bf16 v[82:85], v[238:241], v[204:207], v[82:85]
	v_mfma_f32_16x16x32_bf16 v[74:77], v[246:249], v[204:207], v[74:77]
	v_mfma_f32_16x16x32_bf16 v[70:73], v[238:241], v[212:215], v[70:73]
	v_mfma_f32_16x16x32_bf16 v[66:69], v[246:249], v[212:215], v[66:69]
	s_mov_b32 m0, s18
	v_lshl_add_u64 v[220:221], v[228:229], 0, s[10:11]
	s_barrier
; #define PG8_STAGE(bufoff, gbase, voff) do { _Pragma("unroll") for (int _i = 0; _i < 2; ++_i) \
;     __builtin_amdgcn_global_load_lds((const unsigned*)((const char*)(gbase) + (voff)[_i]), (PG8_LAS unsigned*)(lds + (bufoff) + ldsw + _i * 8192), 16, 0, 0); } while (0)
; #define PG8_LDA(dst, b, h) do { _Pragma("unroll") for (int m = 0; m < 4; ++m) _Pragma("unroll") for (int k = 0; k < 2; ++k) dst[m][k] = *(const PG8_LAS bf16x8*)(lds + PG8_SA(b, h) + aoff + m * 2048 + k * 1024); } while (0)
; #define PG8_MMA(ai, bj, At, Bt) do { __builtin_amdgcn_s_setprio(1); _Pragma("unroll") for (int m = 0; m < 4; ++m) _Pragma("unroll") for (int n = 0; n < 2; ++n) _Pragma("unroll") for (int k = 0; k < 2; ++k) \
;     acc[ai][bj][m][n] = __builtin_amdgcn_mfma_f32_16x16x32_bf16(Bt[n][k], At[m][k], acc[ai][bj][m][n], 0, 0, 0); __builtin_amdgcn_s_setprio(0); } while (0)
; #define PG8_WAIT_V(n) asm volatile("s_waitcnt vmcnt(" #n ")" ::: "memory")
; #define PG8_WAIT_L(n) asm volatile("s_waitcnt lgkmcnt(" #n ")" ::: "memory")
; #define PG8_BAR __builtin_amdgcn_s_barrier()
; #define PG8_SCHED __builtin_amdgcn_sched_barrier(0)
; #define PG8_RTAB_LOAD(var, unit) do { if constexpr (Epi::NEEDS_R) { var = *(const uint4*)(E.ssq + (size_t)((unit).pm * BM + (tid >> 1)) * 16 + (tid & 1) * 8); } } while (0)
; template <class Epi>
; DI void gemm_phase(const bf16_t* __restrict__ gA, const bf16_t* __restrict__ gBt, int M, int N, int K, const Epi& E, char* lds_generic) {
;     ...
;       PG8_LDA(At, 1, 1); PG8_STAGE(PG8_SA(1, 0), a3, voffA);
;       PG8_BAR; PG8_WAIT_L(0); PG8_MMA(1, 0, At, B0); PG8_BAR; PG8_SCHED;
;       PG8_STAGE(PG8_SB(1, 1), b3 + hstep, voffB);
;       PG8_WAIT_V(6); PG8_BAR; PG8_MMA(1, 1, At, B1); PG8_BAR;
;     }
;     uint4 rtn_ = {0u, 0u, 0u, 0u};
;     if (has_next) PG8_RTAB_LOAD(rtn_, nxt);
	ds_read_b128 v[184:187], v154 offset:49152
	ds_read_b128 v[188:191], v154 offset:50176
	ds_read_b128 v[192:195], v154 offset:51200
	ds_read_b128 v[196:199], v154 offset:52224
	ds_read_b128 v[200:203], v154 offset:53248
	ds_read_b128 v[204:207], v154 offset:54272
	ds_read_b128 v[208:211], v154 offset:55296
	ds_read_b128 v[212:215], v154 offset:56320
	global_load_lds_dwordx4 v[220:221], off
	v_lshl_add_u64 v[220:221], v[226:227], 0, s[10:11]
	s_mov_b32 m0, s19
	s_nop 0
	global_load_lds_dwordx4 v[220:221], off
	s_barrier
	s_waitcnt lgkmcnt(0)
	s_waitcnt lgkmcnt(0)
	v_mfma_f32_16x16x32_bf16 v[62:65], v[130:133], v[184:187], v[62:65]
	v_mfma_f32_16x16x32_bf16 v[58:61], v[176:179], v[184:187], v[58:61]
	v_mfma_f32_16x16x32_bf16 v[54:57], v[130:133], v[192:195], v[54:57]
	v_mfma_f32_16x16x32_bf16 v[46:49], v[176:179], v[192:195], v[46:49]
	v_mfma_f32_16x16x32_bf16 v[34:37], v[130:133], v[200:203], v[34:37]
	v_mfma_f32_16x16x32_bf16 v[26:29], v[176:179], v[200:203], v[26:29]
	v_mfma_f32_16x16x32_bf16 v[22:25], v[130:133], v[208:211], v[22:25]
	v_mfma_f32_16x16x32_bf16 v[14:17], v[176:179], v[208:211], v[14:17]
	v_mfma_f32_16x16x32_bf16 v[62:65], v[146:149], v[188:191], v[62:65]
	v_mfma_f32_16x16x32_bf16 v[58:61], v[180:183], v[188:191], v[58:61]
	v_mfma_f32_16x16x32_bf16 v[54:57], v[146:149], v[196:199], v[54:57]
	v_mfma_f32_16x16x32_bf16 v[46:49], v[180:183], v[196:199], v[46:49]
	v_mfma_f32_16x16x32_bf16 v[34:37], v[146:149], v[204:207], v[34:37]
	v_mfma_f32_16x16x32_bf16 v[26:29], v[180:183], v[204:207], v[26:29]
	v_mfma_f32_16x16x32_bf16 v[22:25], v[146:149], v[212:215], v[22:25]
	v_mfma_f32_16x16x32_bf16 v[14:17], v[180:183], v[212:215], v[14:17]
	s_barrier
	s_add_u32 s28, s28, 0x40080
	s_addc_u32 s29, s29, 0
	s_mov_b32 m0, s20
	v_lshl_add_u64 v[130:131], s[28:29], 0, v[0:1]
	global_load_lds_dwordx4 v[130:131], off
	v_lshl_add_u64 v[130:131], s[28:29], 0, v[138:139]
	s_mov_b32 m0, s21
	s_nop 0
	global_load_lds_dwordx4 v[130:131], off
	s_waitcnt vmcnt(6)
	s_barrier
	v_mfma_f32_16x16x32_bf16 v[50:53], v[216:219], v[184:187], v[50:53]
	v_mfma_f32_16x16x32_bf16 v[42:45], v[242:245], v[184:187], v[42:45]
	v_mfma_f32_16x16x32_bf16 v[38:41], v[216:219], v[192:195], v[38:41]
	v_mfma_f32_16x16x32_bf16 v[30:33], v[242:245], v[192:195], v[30:33]
	v_mfma_f32_16x16x32_bf16 v[18:21], v[216:219], v[200:203], v[18:21]
	v_mfma_f32_16x16x32_bf16 v[10:13], v[242:245], v[200:203], v[10:13]
	v_mfma_f32_16x16x32_bf16 v[6:9], v[216:219], v[208:211], v[6:9]
	v_mfma_f32_16x16x32_bf16 v[2:5], v[242:245], v[208:211], v[2:5]
	v_mfma_f32_16x16x32_bf16 v[50:53], v[238:241], v[188:191], v[50:53]
	v_mfma_f32_16x16x32_bf16 v[42:45], v[246:249], v[188:191], v[42:45]
	v_mfma_f32_16x16x32_bf16 v[38:41], v[238:241], v[196:199], v[38:41]
	v_mfma_f32_16x16x32_bf16 v[30:33], v[246:249], v[196:199], v[30:33]
	v_mfma_f32_16x16x32_bf16 v[18:21], v[238:241], v[204:207], v[18:21]
	v_mfma_f32_16x16x32_bf16 v[10:13], v[246:249], v[204:207], v[10:13]
	v_mfma_f32_16x16x32_bf16 v[6:9], v[238:241], v[212:215], v[6:9]
	v_mfma_f32_16x16x32_bf16 v[2:5], v[246:249], v[212:215], v[2:5]
	s_add_i32 s62, s62, 2
	s_add_u32 s80, s80, 0x100
	s_addc_u32 s81, s81, 0
	s_add_u32 s60, s60, 0x100
	s_addc_u32 s61, s61, 0
	s_cmp_gt_u32 s62, 13
	s_barrier
	s_cbranch_scc0 .LBB0_137
	v_mov_b32_e32 v130, 0
	s_and_b64 vcc, exec, s[38:39]
	v_mov_b32_e32 v131, 0
	v_mov_b32_e32 v132, 0
	v_mov_b32_e32 v133, 0
	s_cbranch_vccz .LBB0_140
	v_lshl_add_u32 v130, s26, 8, v150
	v_ashrrev_i32_e32 v131, 31, v130
	v_lshlrev_b64 v[130:131], 5, v[130:131]
	v_lshl_add_u64 v[130:131], v[140:141], 0, v[130:131]
	global_load_dwordx4 v[130:133], v[130:131], off

; #define PG8_STAGE(bufoff, gbase, voff) do { _Pragma("unroll") for (int _i = 0; _i < 2; ++_i) \
;     __builtin_amdgcn_global_load_lds((const unsigned*)((const char*)(gbase) + (voff)[_i]), (PG8_LAS unsigned*)(lds + (bufoff) + ldsw + _i * 8192), 16, 0, 0); } while (0)
; #define PG8_LDA(dst, b, h) do { _Pragma("unroll") for (int m = 0; m < 4; ++m) _Pragma("unroll") for (int k = 0; k < 2; ++k) dst[m][k] = *(const PG8_LAS bf16x8*)(lds + PG8_SA(b, h) + aoff + m * 2048 + k * 1024); } while (0)
; #define PG8_LDB(dst, b, h) do { _Pragma("unroll") for (int n = 0; n < 2; ++n) _Pragma("unroll") for (int k = 0; k < 2; ++k) dst[n][k] = *(const PG8_LAS bf16x8*)(lds + PG8_SB(b, h) + boff + n * 2048 + k * 1024); } while (0)
; #define PG8_MMA(ai, bj, At, Bt) do { __builtin_amdgcn_s_setprio(1); _Pragma("unroll") for (int m = 0; m < 4; ++m) _Pragma("unroll") for (int n = 0; n < 2; ++n) _Pragma("unroll") for (int k = 0; k < 2; ++k) \
;     acc[ai][bj][m][n] = __builtin_amdgcn_mfma_f32_16x16x32_bf16(Bt[n][k], At[m][k], acc[ai][bj][m][n], 0, 0, 0); __builtin_amdgcn_s_setprio(0); } while (0)
; #define PG8_WAIT_V(n) asm volatile("s_waitcnt vmcnt(" #n ")" ::: "memory")
; #define PG8_WAIT_L(n) asm volatile("s_waitcnt lgkmcnt(" #n ")" ::: "memory")
; #define PG8_BAR __builtin_amdgcn_s_barrier()
; #define PG8_SCHED __builtin_amdgcn_sched_barrier(0)
; template <class Epi>
; DI void gemm_phase(const bf16_t* __restrict__ gA, const bf16_t* __restrict__ gBt, int M, int N, int K, const Epi& E, char* lds_generic) {
;     ...
;       const bool last = (t == nt - 2);
;       const char* a1 = cA + (size_t)(t + 1) * kstep;
;       const char* a2 = last ? nA : cA + (size_t)(t + 2) * kstep; const char* b2 = last ? nB : cB + (size_t)(t + 2) * kstep;
;       const char* a3 = a2 + kstep; const char* b3 = b2 + kstep;
;       PG8_LDB(B0, 0, 0); PG8_SCHED; PG8_LDA(At, 0, 0); PG8_STAGE(PG8_SA(1, 1), a1 + hstep, voffA);
;       PG8_WAIT_L(8); PG8_BAR; PG8_WAIT_L(0); PG8_MMA(0, 0, At, B0); PG8_BAR; PG8_SCHED;
;       PG8_LDB(B1, 0, 1); PG8_STAGE(PG8_SB(0, 0), b2, voffB);
;       PG8_BAR; PG8_WAIT_L(0); PG8_MMA(0, 1, At, B1); PG8_BAR;
;       PG8_LDA(At, 0, 1); PG8_STAGE(PG8_SA(0, 0), a2, voffA);
;       PG8_BAR; PG8_WAIT_L(0); PG8_MMA(1, 0, At, B0); PG8_BAR; PG8_SCHED;
;       PG8_STAGE(PG8_SB(0, 1), b2 + hstep, voffB);
;       PG8_WAIT_V(6); PG8_BAR; PG8_MMA(1, 1, At, B1); PG8_BAR;
.LBB0_159:
	v_or_b32_e32 v130, 0x10000, v155
	v_add_u32_e32 v146, 0x10400, v155
	v_add_u32_e32 v158, 0x10800, v155
	ds_read_b128 v[130:133], v130
	ds_read_b128 v[146:149], v146
	v_add_u32_e32 v163, 0x10c00, v155
	ds_read_b128 v[158:161], v158
	ds_read_b128 v[166:169], v163
	s_add_u32 s23, s80, 0xfffc0080
	s_addc_u32 s24, s81, -1
	s_cmp_eq_u32 s22, 12
	s_cselect_b32 s31, s27, s24
	s_cselect_b32 s30, s58, s23
	s_cselect_b32 s29, s1, s61
	s_cselect_b32 s28, s59, s60
	v_lshl_add_u64 v[202:203], s[80:81], 0, v[142:143]
	s_add_i32 m0, s5, 0xc000
	ds_read_b128 v[170:173], v154
	ds_read_b128 v[174:177], v154 offset:1024
	ds_read_b128 v[178:181], v154 offset:2048
	ds_read_b128 v[182:185], v154 offset:3072
	ds_read_b128 v[186:189], v154 offset:4096
	ds_read_b128 v[190:193], v154 offset:5120
	ds_read_b128 v[194:197], v154 offset:6144
	ds_read_b128 v[198:201], v154 offset:7168
	global_load_lds_dwordx4 v[202:203], off
	v_lshl_add_u64 v[202:203], s[80:81], 0, v[144:145]
	s_add_i32 m0, s5, 0xe000
	s_nop 0
	global_load_lds_dwordx4 v[202:203], off
	s_waitcnt lgkmcnt(8)
	s_barrier
	s_waitcnt lgkmcnt(0)
	s_waitcnt lgkmcnt(0)
	v_mfma_f32_16x16x32_bf16 v[126:129], v[130:133], v[170:173], v[126:129]
	v_mfma_f32_16x16x32_bf16 v[122:125], v[158:161], v[170:173], v[122:125]
	v_mfma_f32_16x16x32_bf16 v[118:121], v[130:133], v[178:181], v[118:121]
	v_mfma_f32_16x16x32_bf16 v[110:113], v[158:161], v[178:181], v[110:113]
	v_mfma_f32_16x16x32_bf16 v[98:101], v[130:133], v[186:189], v[98:101]
	v_mfma_f32_16x16x32_bf16 v[90:93], v[158:161], v[186:189], v[90:93]
	v_mfma_f32_16x16x32_bf16 v[86:89], v[130:133], v[194:197], v[86:89]
	v_mfma_f32_16x16x32_bf16 v[78:81], v[158:161], v[194:197], v[78:81]
	v_mfma_f32_16x16x32_bf16 v[126:129], v[146:149], v[174:177], v[126:129]
	v_mfma_f32_16x16x32_bf16 v[122:125], v[166:169], v[174:177], v[122:125]
	v_mfma_f32_16x16x32_bf16 v[118:121], v[146:149], v[182:185], v[118:121]
	v_mfma_f32_16x16x32_bf16 v[110:113], v[166:169], v[182:185], v[110:113]
	v_mfma_f32_16x16x32_bf16 v[98:101], v[146:149], v[190:193], v[98:101]
	v_mfma_f32_16x16x32_bf16 v[90:93], v[166:169], v[190:193], v[90:93]
	v_mfma_f32_16x16x32_bf16 v[86:89], v[146:149], v[198:201], v[86:89]
	v_mfma_f32_16x16x32_bf16 v[78:81], v[166:169], v[198:201], v[78:81]
	s_barrier
	v_or_b32_e32 v163, 0x14000, v155
	s_mov_b32 m0, s6
	v_add_u32_e32 v165, 0x14400, v155
	ds_read_b128 v[202:205], v163
	ds_read_b128 v[206:209], v165
	v_add_u32_e32 v163, 0x14800, v155
	v_lshl_add_u64 v[218:219], s[28:29], 0, v[0:1]
	v_add_u32_e32 v165, 0x14c00, v155
	ds_read_b128 v[210:213], v163
	ds_read_b128 v[214:217], v165
	global_load_lds_dwordx4 v[218:219], off
	v_lshl_add_u64 v[220:221], s[28:29], 0, v[138:139]
	s_mov_b32 m0, s7
	s_nop 0
	global_load_lds_dwordx4 v[220:221], off
	s_barrier
	s_waitcnt lgkmcnt(0)
	s_waitcnt lgkmcnt(0)
	v_mfma_f32_16x16x32_bf16 v[114:117], v[202:205], v[170:173], v[114:117]
	v_mfma_f32_16x16x32_bf16 v[106:109], v[210:213], v[170:173], v[106:109]
	v_mfma_f32_16x16x32_bf16 v[102:105], v[202:205], v[178:181], v[102:105]
	v_mfma_f32_16x16x32_bf16 v[94:97], v[210:213], v[178:181], v[94:97]
	v_mfma_f32_16x16x32_bf16 v[82:85], v[202:205], v[186:189], v[82:85]
	v_mfma_f32_16x16x32_bf16 v[74:77], v[210:213], v[186:189], v[74:77]
	v_mfma_f32_16x16x32_bf16 v[70:73], v[202:205], v[194:197], v[70:73]
	v_mfma_f32_16x16x32_bf16 v[66:69], v[210:213], v[194:197], v[66:69]
	v_mfma_f32_16x16x32_bf16 v[114:117], v[206:209], v[174:177], v[114:117]
	v_mfma_f32_16x16x32_bf16 v[106:109], v[214:217], v[174:177], v[106:109]
	v_mfma_f32_16x16x32_bf16 v[102:105], v[206:209], v[182:185], v[102:105]
	v_mfma_f32_16x16x32_bf16 v[94:97], v[214:217], v[182:185], v[94:97]
	v_mfma_f32_16x16x32_bf16 v[82:85], v[206:209], v[190:193], v[82:85]
	v_mfma_f32_16x16x32_bf16 v[74:77], v[214:217], v[190:193], v[74:77]
	v_mfma_f32_16x16x32_bf16 v[70:73], v[206:209], v[198:201], v[70:73]
	v_mfma_f32_16x16x32_bf16 v[66:69], v[214:217], v[198:201], v[66:69]
	s_mov_b32 m0, s5
	v_lshl_add_u64 v[238:239], s[30:31], 0, v[134:135]
	s_barrier
	ds_read_b128 v[170:173], v154 offset:16384
	ds_read_b128 v[174:177], v154 offset:17408
	ds_read_b128 v[178:181], v154 offset:18432
	ds_read_b128 v[182:185], v154 offset:19456
	ds_read_b128 v[186:189], v154 offset:20480
	ds_read_b128 v[190:193], v154 offset:21504
	ds_read_b128 v[194:197], v154 offset:22528
	ds_read_b128 v[198:201], v154 offset:23552
	global_load_lds_dwordx4 v[238:239], off
	v_lshl_add_u64 v[240:241], s[30:31], 0, v[136:137]
	s_mov_b32 m0, s8
	s_nop 0
	global_load_lds_dwordx4 v[240:241], off
	s_barrier
	s_waitcnt lgkmcnt(0)
	s_waitcnt lgkmcnt(0)
	v_mfma_f32_16x16x32_bf16 v[62:65], v[130:133], v[170:173], v[62:65]
	v_mfma_f32_16x16x32_bf16 v[58:61], v[158:161], v[170:173], v[58:61]
	v_mfma_f32_16x16x32_bf16 v[54:57], v[130:133], v[178:181], v[54:57]
	v_mfma_f32_16x16x32_bf16 v[46:49], v[158:161], v[178:181], v[46:49]
	v_mfma_f32_16x16x32_bf16 v[34:37], v[130:133], v[186:189], v[34:37]
	v_mfma_f32_16x16x32_bf16 v[26:29], v[158:161], v[186:189], v[26:29]
	v_mfma_f32_16x16x32_bf16 v[22:25], v[130:133], v[194:197], v[22:25]
	v_mfma_f32_16x16x32_bf16 v[14:17], v[158:161], v[194:197], v[14:17]
	v_mfma_f32_16x16x32_bf16 v[62:65], v[146:149], v[174:177], v[62:65]
	v_mfma_f32_16x16x32_bf16 v[58:61], v[166:169], v[174:177], v[58:61]
	v_mfma_f32_16x16x32_bf16 v[54:57], v[146:149], v[182:185], v[54:57]
	v_mfma_f32_16x16x32_bf16 v[46:49], v[166:169], v[182:185], v[46:49]
	v_mfma_f32_16x16x32_bf16 v[34:37], v[146:149], v[190:193], v[34:37]
	v_mfma_f32_16x16x32_bf16 v[26:29], v[166:169], v[190:193], v[26:29]
	v_mfma_f32_16x16x32_bf16 v[22:25], v[146:149], v[198:201], v[22:25]
	v_mfma_f32_16x16x32_bf16 v[14:17], v[166:169], v[198:201], v[14:17]
	s_barrier
; #define PG8_STAGE(bufoff, gbase, voff) do { _Pragma("unroll") for (int _i = 0; _i < 2; ++_i) \
;     __builtin_amdgcn_global_load_lds((const unsigned*)((const char*)(gbase) + (voff)[_i]), (PG8_LAS unsigned*)(lds + (bufoff) + ldsw + _i * 8192), 16, 0, 0); } while (0)
; #define PG8_LDA(dst, b, h) do { _Pragma("unroll") for (int m = 0; m < 4; ++m) _Pragma("unroll") for (int k = 0; k < 2; ++k) dst[m][k] = *(const PG8_LAS bf16x8*)(lds + PG8_SA(b, h) + aoff + m * 2048 + k * 1024); } while (0)
; #define PG8_LDB(dst, b, h) do { _Pragma("unroll") for (int n = 0; n < 2; ++n) _Pragma("unroll") for (int k = 0; k < 2; ++k) dst[n][k] = *(const PG8_LAS bf16x8*)(lds + PG8_SB(b, h) + boff + n * 2048 + k * 1024); } while (0)
; #define PG8_MMA(ai, bj, At, Bt) do { __builtin_amdgcn_s_setprio(1); _Pragma("unroll") for (int m = 0; m < 4; ++m) _Pragma("unroll") for (int n = 0; n < 2; ++n) _Pragma("unroll") for (int k = 0; k < 2; ++k) \
;     acc[ai][bj][m][n] = __builtin_amdgcn_mfma_f32_16x16x32_bf16(Bt[n][k], At[m][k], acc[ai][bj][m][n], 0, 0, 0); __builtin_amdgcn_s_setprio(0); } while (0)
; #define PG8_WAIT_V(n) asm volatile("s_waitcnt vmcnt(" #n ")" ::: "memory")
; #define PG8_WAIT_L(n) asm volatile("s_waitcnt lgkmcnt(" #n ")" ::: "memory")
; #define PG8_BAR __builtin_amdgcn_s_barrier()
; #define PG8_SCHED __builtin_amdgcn_sched_barrier(0)
; template <class Epi>
; DI void gemm_phase(const bf16_t* __restrict__ gA, const bf16_t* __restrict__ gBt, int M, int N, int K, const Epi& E, char* lds_generic) {
;     ...
;       PG8_WAIT_V(6); PG8_BAR; PG8_MMA(1, 1, At, B1); PG8_BAR;
;       PG8_LDB(B0, 1, 0); PG8_SCHED; PG8_LDA(At, 1, 0); PG8_STAGE(PG8_SA(0, 1), a2 + hstep, voffA);
;       PG8_WAIT_L(8); PG8_BAR; PG8_WAIT_L(0); PG8_MMA(0, 0, At, B0); PG8_BAR; PG8_SCHED;
;       PG8_LDB(B1, 1, 1); PG8_STAGE(PG8_SB(1, 0), b3, voffB);
;       PG8_BAR; PG8_WAIT_L(0); PG8_MMA(0, 1, At, B1); PG8_BAR;
;       PG8_LDA(At, 1, 1); PG8_STAGE(PG8_SA(1, 0), a3, voffA);
;       PG8_BAR; PG8_WAIT_L(0); PG8_MMA(1, 0, At, B0); PG8_BAR; PG8_SCHED;
;       PG8_STAGE(PG8_SB(1, 1), b3 + hstep, voffB);
	s_add_u32 s82, s28, 0x40000
	s_addc_u32 s83, s29, 0
	s_mov_b32 m0, s9
	v_lshl_add_u64 v[130:131], s[82:83], 0, v[0:1]
	global_load_lds_dwordx4 v[130:131], off
	v_lshl_add_u64 v[130:131], s[82:83], 0, v[138:139]
	s_mov_b32 m0, s12
	s_nop 0
	global_load_lds_dwordx4 v[130:131], off
	s_waitcnt vmcnt(6)
	s_barrier
	v_mfma_f32_16x16x32_bf16 v[50:53], v[202:205], v[170:173], v[50:53]
	v_mfma_f32_16x16x32_bf16 v[42:45], v[210:213], v[170:173], v[42:45]
	v_mfma_f32_16x16x32_bf16 v[38:41], v[202:205], v[178:181], v[38:41]
	v_mfma_f32_16x16x32_bf16 v[30:33], v[210:213], v[178:181], v[30:33]
	v_mfma_f32_16x16x32_bf16 v[18:21], v[202:205], v[186:189], v[18:21]
	v_mfma_f32_16x16x32_bf16 v[10:13], v[210:213], v[186:189], v[10:13]
	v_mfma_f32_16x16x32_bf16 v[6:9], v[202:205], v[194:197], v[6:9]
	v_mfma_f32_16x16x32_bf16 v[2:5], v[210:213], v[194:197], v[2:5]
	v_mfma_f32_16x16x32_bf16 v[50:53], v[206:209], v[174:177], v[50:53]
	v_mfma_f32_16x16x32_bf16 v[42:45], v[214:217], v[174:177], v[42:45]
	v_mfma_f32_16x16x32_bf16 v[38:41], v[206:209], v[182:185], v[38:41]
	v_mfma_f32_16x16x32_bf16 v[30:33], v[214:217], v[182:185], v[30:33]
	v_mfma_f32_16x16x32_bf16 v[18:21], v[206:209], v[190:193], v[18:21]
	v_mfma_f32_16x16x32_bf16 v[10:13], v[214:217], v[190:193], v[10:13]
	v_mfma_f32_16x16x32_bf16 v[6:9], v[206:209], v[198:201], v[6:9]
	v_mfma_f32_16x16x32_bf16 v[2:5], v[214:217], v[198:201], v[2:5]
	v_or_b32_e32 v130, 0x18000, v155
	v_add_u32_e32 v146, 0x18400, v155
	v_add_u32_e32 v158, 0x18800, v155
	s_barrier
	ds_read_b128 v[130:133], v130
	ds_read_b128 v[146:149], v146
	v_add_u32_e32 v163, 0x18c00, v155
	ds_read_b128 v[158:161], v158
	ds_read_b128 v[166:169], v163
	s_add_u32 s30, s30, 0x40000
	s_addc_u32 s31, s31, 0
	s_mov_b32 m0, s13
	v_lshl_add_u64 v[202:203], s[30:31], 0, v[134:135]
	ds_read_b128 v[170:173], v154 offset:32768
	ds_read_b128 v[174:177], v154 offset:33792
	ds_read_b128 v[178:181], v154 offset:34816
	ds_read_b128 v[182:185], v154 offset:35840
	ds_read_b128 v[186:189], v154 offset:36864
	ds_read_b128 v[190:193], v154 offset:37888
	ds_read_b128 v[194:197], v154 offset:38912
	ds_read_b128 v[198:201], v154 offset:39936
	global_load_lds_dwordx4 v[202:203], off
	v_lshl_add_u64 v[202:203], s[30:31], 0, v[136:137]
	s_mov_b32 m0, s14
	s_nop 0
	global_load_lds_dwordx4 v[202:203], off
	s_waitcnt lgkmcnt(8)
	s_barrier
	s_waitcnt lgkmcnt(0)
	s_waitcnt lgkmcnt(0)
	v_mfma_f32_16x16x32_bf16 v[126:129], v[130:133], v[170:173], v[126:129]
	v_mfma_f32_16x16x32_bf16 v[122:125], v[158:161], v[170:173], v[122:125]
	v_mfma_f32_16x16x32_bf16 v[118:121], v[130:133], v[178:181], v[118:121]
	v_mfma_f32_16x16x32_bf16 v[110:113], v[158:161], v[178:181], v[110:113]
	v_mfma_f32_16x16x32_bf16 v[98:101], v[130:133], v[186:189], v[98:101]
	v_mfma_f32_16x16x32_bf16 v[90:93], v[158:161], v[186:189], v[90:93]
	v_mfma_f32_16x16x32_bf16 v[86:89], v[130:133], v[194:197], v[86:89]
	v_mfma_f32_16x16x32_bf16 v[78:81], v[158:161], v[194:197], v[78:81]
	v_mfma_f32_16x16x32_bf16 v[126:129], v[146:149], v[174:177], v[126:129]
	v_mfma_f32_16x16x32_bf16 v[122:125], v[166:169], v[174:177], v[122:125]
	v_mfma_f32_16x16x32_bf16 v[118:121], v[146:149], v[182:185], v[118:121]
	v_mfma_f32_16x16x32_bf16 v[110:113], v[166:169], v[182:185], v[110:113]
	v_mfma_f32_16x16x32_bf16 v[98:101], v[146:149], v[190:193], v[98:101]
	v_mfma_f32_16x16x32_bf16 v[90:93], v[166:169], v[190:193], v[90:93]
	v_mfma_f32_16x16x32_bf16 v[86:89], v[146:149], v[198:201], v[86:89]
	v_mfma_f32_16x16x32_bf16 v[78:81], v[166:169], v[198:201], v[78:81]
	s_barrier
	v_or_b32_e32 v163, 0x1c000, v155
	s_mov_b32 m0, s15
	v_add_u32_e32 v165, 0x1c400, v155
	ds_read_b128 v[202:205], v163
	ds_read_b128 v[206:209], v165
	v_add_u32_e32 v163, 0x1c800, v155
	v_lshl_add_u64 v[218:219], v[218:219], 0, s[10:11]
	v_add_u32_e32 v165, 0x1cc00, v155
	ds_read_b128 v[210:213], v163
	ds_read_b128 v[214:217], v165
	global_load_lds_dwordx4 v[218:219], off
	v_lshl_add_u64 v[218:219], v[220:221], 0, s[10:11]
	s_mov_b32 m0, s16
	s_nop 0
	global_load_lds_dwordx4 v[218:219], off
	s_barrier
; #define PG8_STAGE(bufoff, gbase, voff) do { _Pragma("unroll") for (int _i = 0; _i < 2; ++_i) \
;     __builtin_amdgcn_global_load_lds((const unsigned*)((const char*)(gbase) + (voff)[_i]), (PG8_LAS unsigned*)(lds + (bufoff) + ldsw + _i * 8192), 16, 0, 0); } while (0)
; #define PG8_LDA(dst, b, h) do { _Pragma("unroll") for (int m = 0; m < 4; ++m) _Pragma("unroll") for (int k = 0; k < 2; ++k) dst[m][k] = *(const PG8_LAS bf16x8*)(lds + PG8_SA(b, h) + aoff + m * 2048 + k * 1024); } while (0)
; #define PG8_MMA(ai, bj, At, Bt) do { __builtin_amdgcn_s_setprio(1); _Pragma("unroll") for (int m = 0; m < 4; ++m) _Pragma("unroll") for (int n = 0; n < 2; ++n) _Pragma("unroll") for (int k = 0; k < 2; ++k) \
;     acc[ai][bj][m][n] = __builtin_amdgcn_mfma_f32_16x16x32_bf16(Bt[n][k], At[m][k], acc[ai][bj][m][n], 0, 0, 0); __builtin_amdgcn_s_setprio(0); } while (0)
; #define PG8_WAIT_V(n) asm volatile("s_waitcnt vmcnt(" #n ")" ::: "memory")
; #define PG8_WAIT_L(n) asm volatile("s_waitcnt lgkmcnt(" #n ")" ::: "memory")
; #define PG8_BAR __builtin_amdgcn_s_barrier()
; #define PG8_SCHED __builtin_amdgcn_sched_barrier(0)
; #define PG8_RTAB_LOAD(var, unit) do { if constexpr (Epi::NEEDS_R) { var = *(const uint4*)(E.ssq + (size_t)((unit).pm * BM + (tid >> 1)) * 16 + (tid & 1) * 8); } } while (0)
; template <class Epi>
; DI void gemm_phase(const bf16_t* __restrict__ gA, const bf16_t* __restrict__ gBt, int M, int N, int K, const Epi& E, char* lds_generic) {
;     ...
;       PG8_BAR; PG8_WAIT_L(0); PG8_MMA(0, 1, At, B1); PG8_BAR;
;       PG8_LDA(At, 1, 1); PG8_STAGE(PG8_SA(1, 0), a3, voffA);
;       PG8_BAR; PG8_WAIT_L(0); PG8_MMA(1, 0, At, B0); PG8_BAR; PG8_SCHED;
;       PG8_STAGE(PG8_SB(1, 1), b3 + hstep, voffB);
;       PG8_WAIT_V(6); PG8_BAR; PG8_MMA(1, 1, At, B1); PG8_BAR;
;     }
;     uint4 rtn_ = {0u, 0u, 0u, 0u};
;     if (has_next) PG8_RTAB_LOAD(rtn_, nxt);
	s_waitcnt lgkmcnt(0)
	s_waitcnt lgkmcnt(0)
	v_mfma_f32_16x16x32_bf16 v[114:117], v[202:205], v[170:173], v[114:117]
	v_mfma_f32_16x16x32_bf16 v[106:109], v[210:213], v[170:173], v[106:109]
	v_mfma_f32_16x16x32_bf16 v[102:105], v[202:205], v[178:181], v[102:105]
	v_mfma_f32_16x16x32_bf16 v[94:97], v[210:213], v[178:181], v[94:97]
	v_mfma_f32_16x16x32_bf16 v[82:85], v[202:205], v[186:189], v[82:85]
	v_mfma_f32_16x16x32_bf16 v[74:77], v[210:213], v[186:189], v[74:77]
	v_mfma_f32_16x16x32_bf16 v[70:73], v[202:205], v[194:197], v[70:73]
	v_mfma_f32_16x16x32_bf16 v[66:69], v[210:213], v[194:197], v[66:69]
	v_mfma_f32_16x16x32_bf16 v[114:117], v[206:209], v[174:177], v[114:117]
	v_mfma_f32_16x16x32_bf16 v[106:109], v[214:217], v[174:177], v[106:109]
	v_mfma_f32_16x16x32_bf16 v[102:105], v[206:209], v[182:185], v[102:105]
	v_mfma_f32_16x16x32_bf16 v[94:97], v[214:217], v[182:185], v[94:97]
	v_mfma_f32_16x16x32_bf16 v[82:85], v[206:209], v[190:193], v[82:85]
	v_mfma_f32_16x16x32_bf16 v[74:77], v[214:217], v[190:193], v[74:77]
	v_mfma_f32_16x16x32_bf16 v[70:73], v[206:209], v[198:201], v[70:73]
	v_mfma_f32_16x16x32_bf16 v[66:69], v[214:217], v[198:201], v[66:69]
	s_mov_b32 m0, s18
	v_lshl_add_u64 v[218:219], v[238:239], 0, s[10:11]
	s_barrier
	ds_read_b128 v[170:173], v154 offset:49152
	ds_read_b128 v[174:177], v154 offset:50176
	ds_read_b128 v[178:181], v154 offset:51200
	ds_read_b128 v[182:185], v154 offset:52224
	ds_read_b128 v[186:189], v154 offset:53248
	ds_read_b128 v[190:193], v154 offset:54272
	ds_read_b128 v[194:197], v154 offset:55296
	ds_read_b128 v[198:201], v154 offset:56320
	global_load_lds_dwordx4 v[218:219], off
	v_lshl_add_u64 v[218:219], v[240:241], 0, s[10:11]
	s_mov_b32 m0, s19
	s_nop 0
	global_load_lds_dwordx4 v[218:219], off
	s_barrier
	s_waitcnt lgkmcnt(0)
	s_waitcnt lgkmcnt(0)
	v_mfma_f32_16x16x32_bf16 v[62:65], v[130:133], v[170:173], v[62:65]
	v_mfma_f32_16x16x32_bf16 v[58:61], v[158:161], v[170:173], v[58:61]
	v_mfma_f32_16x16x32_bf16 v[54:57], v[130:133], v[178:181], v[54:57]
	v_mfma_f32_16x16x32_bf16 v[46:49], v[158:161], v[178:181], v[46:49]
	v_mfma_f32_16x16x32_bf16 v[34:37], v[130:133], v[186:189], v[34:37]
	v_mfma_f32_16x16x32_bf16 v[26:29], v[158:161], v[186:189], v[26:29]
	v_mfma_f32_16x16x32_bf16 v[22:25], v[130:133], v[194:197], v[22:25]
	v_mfma_f32_16x16x32_bf16 v[14:17], v[158:161], v[194:197], v[14:17]
	v_mfma_f32_16x16x32_bf16 v[62:65], v[146:149], v[174:177], v[62:65]
	v_mfma_f32_16x16x32_bf16 v[58:61], v[166:169], v[174:177], v[58:61]
	v_mfma_f32_16x16x32_bf16 v[54:57], v[146:149], v[182:185], v[54:57]
	v_mfma_f32_16x16x32_bf16 v[46:49], v[166:169], v[182:185], v[46:49]
	v_mfma_f32_16x16x32_bf16 v[34:37], v[146:149], v[190:193], v[34:37]
	v_mfma_f32_16x16x32_bf16 v[26:29], v[166:169], v[190:193], v[26:29]
	v_mfma_f32_16x16x32_bf16 v[22:25], v[146:149], v[198:201], v[22:25]
	v_mfma_f32_16x16x32_bf16 v[14:17], v[166:169], v[198:201], v[14:17]
	s_barrier
	s_add_u32 s28, s28, 0x40080
	s_addc_u32 s29, s29, 0
	s_mov_b32 m0, s20
	v_lshl_add_u64 v[130:131], s[28:29], 0, v[0:1]
	global_load_lds_dwordx4 v[130:131], off
	v_lshl_add_u64 v[130:131], s[28:29], 0, v[138:139]
	s_mov_b32 m0, s21
	s_nop 0
	global_load_lds_dwordx4 v[130:131], off
	s_waitcnt vmcnt(6)
	s_barrier
	v_mfma_f32_16x16x32_bf16 v[50:53], v[202:205], v[170:173], v[50:53]
	v_mfma_f32_16x16x32_bf16 v[42:45], v[210:213], v[170:173], v[42:45]
	v_mfma_f32_16x16x32_bf16 v[38:41], v[202:205], v[178:181], v[38:41]
	v_mfma_f32_16x16x32_bf16 v[30:33], v[210:213], v[178:181], v[30:33]
	v_mfma_f32_16x16x32_bf16 v[18:21], v[202:205], v[186:189], v[18:21]
	v_mfma_f32_16x16x32_bf16 v[10:13], v[210:213], v[186:189], v[10:13]
	v_mfma_f32_16x16x32_bf16 v[6:9], v[202:205], v[194:197], v[6:9]
	v_mfma_f32_16x16x32_bf16 v[2:5], v[210:213], v[194:197], v[2:5]
	v_mfma_f32_16x16x32_bf16 v[50:53], v[206:209], v[174:177], v[50:53]
	v_mfma_f32_16x16x32_bf16 v[42:45], v[214:217], v[174:177], v[42:45]
	v_mfma_f32_16x16x32_bf16 v[38:41], v[206:209], v[182:185], v[38:41]
	v_mfma_f32_16x16x32_bf16 v[30:33], v[214:217], v[182:185], v[30:33]
	v_mfma_f32_16x16x32_bf16 v[18:21], v[206:209], v[190:193], v[18:21]
	v_mfma_f32_16x16x32_bf16 v[10:13], v[214:217], v[190:193], v[10:13]
	v_mfma_f32_16x16x32_bf16 v[6:9], v[206:209], v[198:201], v[6:9]
	v_mfma_f32_16x16x32_bf16 v[2:5], v[214:217], v[198:201], v[2:5]
	s_add_i32 s22, s22, 2
	s_add_u32 s80, s80, 0x100
	s_addc_u32 s81, s81, 0
	s_add_u32 s60, s60, 0x100
	s_addc_u32 s61, s61, 0
	s_cmp_gt_u32 s22, 13
	s_barrier
	s_cbranch_scc0 .LBB0_159
	v_mov_b32_e32 v130, 0
	s_and_b64 vcc, exec, s[38:39]
	v_mov_b32_e32 v131, 0
	v_mov_b32_e32 v132, 0
	v_mov_b32_e32 v133, 0
	s_cbranch_vccz .LBB0_162
	v_lshl_add_u32 v130, s26, 8, v150
	v_ashrrev_i32_e32 v131, 31, v130
	v_lshlrev_b64 v[130:131], 5, v[130:131]
	v_lshl_add_u64 v[130:131], v[140:141], 0, v[130:131]
	global_load_dwordx4 v[130:133], v[130:131], off

; #define PG8_STAGE(bufoff, gbase, voff) do { _Pragma("unroll") for (int _i = 0; _i < 2; ++_i) \
;     __builtin_amdgcn_global_load_lds((const unsigned*)((const char*)(gbase) + (voff)[_i]), (PG8_LAS unsigned*)(lds + (bufoff) + ldsw + _i * 8192), 16, 0, 0); } while (0)
; #define PG8_LDA(dst, b, h) do { _Pragma("unroll") for (int m = 0; m < 4; ++m) _Pragma("unroll") for (int k = 0; k < 2; ++k) dst[m][k] = *(const PG8_LAS bf16x8*)(lds + PG8_SA(b, h) + aoff + m * 2048 + k * 1024); } while (0)
; #define PG8_LDB(dst, b, h) do { _Pragma("unroll") for (int n = 0; n < 2; ++n) _Pragma("unroll") for (int k = 0; k < 2; ++k) dst[n][k] = *(const PG8_LAS bf16x8*)(lds + PG8_SB(b, h) + boff + n * 2048 + k * 1024); } while (0)
; #define PG8_MMA(ai, bj, At, Bt) do { __builtin_amdgcn_s_setprio(1); _Pragma("unroll") for (int m = 0; m < 4; ++m) _Pragma("unroll") for (int n = 0; n < 2; ++n) _Pragma("unroll") for (int k = 0; k < 2; ++k) \
;     acc[ai][bj][m][n] = __builtin_amdgcn_mfma_f32_16x16x32_bf16(Bt[n][k], At[m][k], acc[ai][bj][m][n], 0, 0, 0); __builtin_amdgcn_s_setprio(0); } while (0)
; #define PG8_WAIT_L(n) asm volatile("s_waitcnt lgkmcnt(" #n ")" ::: "memory")
; #define PG8_BAR __builtin_amdgcn_s_barrier()
; #define PG8_SCHED __builtin_amdgcn_sched_barrier(0)
; template <class Epi>
; DI void gemm_phase(const bf16_t* __restrict__ gA, const bf16_t* __restrict__ gBt, int M, int N, int K, const Epi& E, char* lds_generic) {
;     ...
;       const bool last = (t == nt - 2);
;       const char* a1 = cA + (size_t)(t + 1) * kstep;
;       const char* a2 = last ? nA : cA + (size_t)(t + 2) * kstep; const char* b2 = last ? nB : cB + (size_t)(t + 2) * kstep;
;       const char* a3 = a2 + kstep; const char* b3 = b2 + kstep;
;       PG8_LDB(B0, 0, 0); PG8_SCHED; PG8_LDA(At, 0, 0); PG8_STAGE(PG8_SA(1, 1), a1 + hstep, voffA);
;       PG8_WAIT_L(8); PG8_BAR; PG8_WAIT_L(0); PG8_MMA(0, 0, At, B0); PG8_BAR; PG8_SCHED;
;       PG8_LDB(B1, 0, 1); PG8_STAGE(PG8_SB(0, 0), b2, voffB);
;       PG8_BAR; PG8_WAIT_L(0); PG8_MMA(0, 1, At, B1); PG8_BAR;
;       PG8_LDA(At, 0, 1); PG8_STAGE(PG8_SA(0, 0), a2, voffA);
;       PG8_BAR; PG8_WAIT_L(0); PG8_MMA(1, 0, At, B0); PG8_BAR; PG8_SCHED;
;       PG8_STAGE(PG8_SB(0, 1), b2 + hstep, voffB);
.LBB0_511:
	v_or_b32_e32 v140, 0x10000, v146
	v_add_u32_e32 v148, 0x10400, v146
	v_add_u32_e32 v152, 0x10800, v146
	v_add_u32_e32 v156, 0x10c00, v146
	ds_read_b128 v[140:143], v140
	ds_read_b128 v[148:151], v148
	ds_read_b128 v[152:155], v152
	ds_read_b128 v[156:159], v156
	s_add_u32 s0, s28, 0xfffc0080
	s_addc_u32 s1, s29, -1
	s_cmp_eq_u32 s60, 12
	s_cselect_b32 s31, s22, s1
	s_cselect_b32 s30, s23, s0
	s_cselect_b32 s1, s27, s59
	s_cselect_b32 s0, s39, s58
	v_lshl_add_u64 v[160:161], s[28:29], 0, v[136:137]
	s_add_i32 m0, s6, 0xc000
	ds_read_b128 v[166:169], v145
	ds_read_b128 v[170:173], v145 offset:1024
	ds_read_b128 v[174:177], v145 offset:2048
	ds_read_b128 v[178:181], v145 offset:3072
	ds_read_b128 v[182:185], v145 offset:4096
	ds_read_b128 v[186:189], v145 offset:5120
	ds_read_b128 v[190:193], v145 offset:6144
	ds_read_b128 v[194:197], v145 offset:7168
	global_load_lds_dwordx4 v[160:161], off
	v_lshl_add_u64 v[160:161], s[28:29], 0, v[138:139]
	s_add_i32 m0, s6, 0xe000
	s_nop 0
	global_load_lds_dwordx4 v[160:161], off
	s_waitcnt lgkmcnt(8)
	s_barrier
	s_waitcnt lgkmcnt(0)
	s_waitcnt lgkmcnt(0)
	v_mfma_f32_16x16x32_bf16 v[118:121], v[140:143], v[166:169], v[118:121]
	v_mfma_f32_16x16x32_bf16 v[110:113], v[152:155], v[166:169], v[110:113]
	v_mfma_f32_16x16x32_bf16 v[90:93], v[140:143], v[174:177], v[90:93]
	v_mfma_f32_16x16x32_bf16 v[82:85], v[152:155], v[174:177], v[82:85]
	v_mfma_f32_16x16x32_bf16 v[62:65], v[140:143], v[182:185], v[62:65]
	v_mfma_f32_16x16x32_bf16 v[50:53], v[152:155], v[182:185], v[50:53]
	v_mfma_f32_16x16x32_bf16 v[42:45], v[140:143], v[190:193], v[42:45]
	v_mfma_f32_16x16x32_bf16 v[22:25], v[152:155], v[190:193], v[22:25]
	v_mfma_f32_16x16x32_bf16 v[118:121], v[148:151], v[170:173], v[118:121]
	v_mfma_f32_16x16x32_bf16 v[110:113], v[156:159], v[170:173], v[110:113]
	v_mfma_f32_16x16x32_bf16 v[90:93], v[148:151], v[178:181], v[90:93]
	v_mfma_f32_16x16x32_bf16 v[82:85], v[156:159], v[178:181], v[82:85]
	v_mfma_f32_16x16x32_bf16 v[62:65], v[148:151], v[186:189], v[62:65]
	v_mfma_f32_16x16x32_bf16 v[50:53], v[156:159], v[186:189], v[50:53]
	v_mfma_f32_16x16x32_bf16 v[42:45], v[148:151], v[194:197], v[42:45]
	v_mfma_f32_16x16x32_bf16 v[22:25], v[156:159], v[194:197], v[22:25]
	s_barrier
	v_or_b32_e32 v160, 0x14000, v146
	v_add_u32_e32 v161, 0x14400, v146
	ds_read_b128 v[198:201], v160
	ds_read_b128 v[202:205], v161
	v_add_u32_e32 v160, 0x14800, v146
	v_add_u32_e32 v161, 0x14c00, v146
	s_mov_b32 m0, s7
	ds_read_b128 v[206:209], v160
	ds_read_b128 v[210:213], v161
	v_lshl_add_u64 v[160:161], s[0:1], 0, v[0:1]
	global_load_lds_dwordx4 v[160:161], off
	v_lshl_add_u64 v[214:215], s[0:1], 0, v[130:131]
	s_mov_b32 m0, s12
	s_nop 0
	global_load_lds_dwordx4 v[214:215], off
	s_barrier
	s_waitcnt lgkmcnt(0)
	s_waitcnt lgkmcnt(0)
	v_mfma_f32_16x16x32_bf16 v[122:125], v[198:201], v[166:169], v[122:125]
	v_mfma_f32_16x16x32_bf16 v[126:129], v[206:209], v[166:169], v[126:129]
	v_mfma_f32_16x16x32_bf16 v[102:105], v[198:201], v[174:177], v[102:105]
	v_mfma_f32_16x16x32_bf16 v[114:117], v[206:209], v[174:177], v[114:117]
	v_mfma_f32_16x16x32_bf16 v[86:89], v[198:201], v[182:185], v[86:89]
	v_mfma_f32_16x16x32_bf16 v[98:101], v[206:209], v[182:185], v[98:101]
	v_mfma_f32_16x16x32_bf16 v[58:61], v[198:201], v[190:193], v[58:61]
	v_mfma_f32_16x16x32_bf16 v[74:77], v[206:209], v[190:193], v[74:77]
	v_mfma_f32_16x16x32_bf16 v[122:125], v[202:205], v[170:173], v[122:125]
	v_mfma_f32_16x16x32_bf16 v[126:129], v[210:213], v[170:173], v[126:129]
	v_mfma_f32_16x16x32_bf16 v[102:105], v[202:205], v[178:181], v[102:105]
	v_mfma_f32_16x16x32_bf16 v[114:117], v[210:213], v[178:181], v[114:117]
	v_mfma_f32_16x16x32_bf16 v[86:89], v[202:205], v[186:189], v[86:89]
	v_mfma_f32_16x16x32_bf16 v[98:101], v[210:213], v[186:189], v[98:101]
	v_mfma_f32_16x16x32_bf16 v[58:61], v[202:205], v[194:197], v[58:61]
	v_mfma_f32_16x16x32_bf16 v[74:77], v[210:213], v[194:197], v[74:77]
	s_mov_b32 m0, s6
	v_lshl_add_u64 v[216:217], s[30:31], 0, v[134:135]
	s_barrier
	ds_read_b128 v[166:169], v145 offset:16384
	ds_read_b128 v[170:173], v145 offset:17408
	ds_read_b128 v[174:177], v145 offset:18432
	ds_read_b128 v[178:181], v145 offset:19456
	ds_read_b128 v[182:185], v145 offset:20480
	ds_read_b128 v[186:189], v145 offset:21504
	ds_read_b128 v[190:193], v145 offset:22528
	ds_read_b128 v[194:197], v145 offset:23552
	global_load_lds_dwordx4 v[216:217], off
	v_lshl_add_u64 v[218:219], s[30:31], 0, v[132:133]
	s_mov_b32 m0, s13
	s_nop 0
	global_load_lds_dwordx4 v[218:219], off
	s_barrier
	s_waitcnt lgkmcnt(0)
	s_waitcnt lgkmcnt(0)
	v_mfma_f32_16x16x32_bf16 v[38:41], v[140:143], v[166:169], v[38:41]
	v_mfma_f32_16x16x32_bf16 v[18:21], v[152:155], v[166:169], v[18:21]
	v_mfma_f32_16x16x32_bf16 v[10:13], v[140:143], v[174:177], v[10:13]
	v_mfma_f32_16x16x32_bf16 v[2:5], v[152:155], v[174:177], v[2:5]
	v_mfma_f32_16x16x32_bf16 v[46:49], v[140:143], v[182:185], v[46:49]
	v_mfma_f32_16x16x32_bf16 v[30:33], v[152:155], v[182:185], v[30:33]
	v_mfma_f32_16x16x32_bf16 v[14:17], v[140:143], v[190:193], v[14:17]
	v_mfma_f32_16x16x32_bf16 v[6:9], v[152:155], v[190:193], v[6:9]
	v_mfma_f32_16x16x32_bf16 v[38:41], v[148:151], v[170:173], v[38:41]
	v_mfma_f32_16x16x32_bf16 v[18:21], v[156:159], v[170:173], v[18:21]
	v_mfma_f32_16x16x32_bf16 v[10:13], v[148:151], v[178:181], v[10:13]
	v_mfma_f32_16x16x32_bf16 v[2:5], v[156:159], v[178:181], v[2:5]
	v_mfma_f32_16x16x32_bf16 v[46:49], v[148:151], v[186:189], v[46:49]
	v_mfma_f32_16x16x32_bf16 v[30:33], v[156:159], v[186:189], v[30:33]
	v_mfma_f32_16x16x32_bf16 v[14:17], v[148:151], v[194:197], v[14:17]
	v_mfma_f32_16x16x32_bf16 v[6:9], v[156:159], v[194:197], v[6:9]
	s_barrier
; #define PG8_STAGE(bufoff, gbase, voff) do { _Pragma("unroll") for (int _i = 0; _i < 2; ++_i) \
;     __builtin_amdgcn_global_load_lds((const unsigned*)((const char*)(gbase) + (voff)[_i]), (PG8_LAS unsigned*)(lds + (bufoff) + ldsw + _i * 8192), 16, 0, 0); } while (0)
; #define PG8_LDA(dst, b, h) do { _Pragma("unroll") for (int m = 0; m < 4; ++m) _Pragma("unroll") for (int k = 0; k < 2; ++k) dst[m][k] = *(const PG8_LAS bf16x8*)(lds + PG8_SA(b, h) + aoff + m * 2048 + k * 1024); } while (0)
; #define PG8_LDB(dst, b, h) do { _Pragma("unroll") for (int n = 0; n < 2; ++n) _Pragma("unroll") for (int k = 0; k < 2; ++k) dst[n][k] = *(const PG8_LAS bf16x8*)(lds + PG8_SB(b, h) + boff + n * 2048 + k * 1024); } while (0)
; #define PG8_MMA(ai, bj, At, Bt) do { __builtin_amdgcn_s_setprio(1); _Pragma("unroll") for (int m = 0; m < 4; ++m) _Pragma("unroll") for (int n = 0; n < 2; ++n) _Pragma("unroll") for (int k = 0; k < 2; ++k) \
;     acc[ai][bj][m][n] = __builtin_amdgcn_mfma_f32_16x16x32_bf16(Bt[n][k], At[m][k], acc[ai][bj][m][n], 0, 0, 0); __builtin_amdgcn_s_setprio(0); } while (0)
; #define PG8_WAIT_V(n) asm volatile("s_waitcnt vmcnt(" #n ")" ::: "memory")
; #define PG8_WAIT_L(n) asm volatile("s_waitcnt lgkmcnt(" #n ")" ::: "memory")
; #define PG8_BAR __builtin_amdgcn_s_barrier()
; #define PG8_SCHED __builtin_amdgcn_sched_barrier(0)
; template <class Epi>
; DI void gemm_phase(const bf16_t* __restrict__ gA, const bf16_t* __restrict__ gBt, int M, int N, int K, const Epi& E, char* lds_generic) {
;     ...
;       PG8_STAGE(PG8_SB(0, 1), b2 + hstep, voffB);
;       PG8_WAIT_V(6); PG8_BAR; PG8_MMA(1, 1, At, B1); PG8_BAR;
;       PG8_LDB(B0, 1, 0); PG8_SCHED; PG8_LDA(At, 1, 0); PG8_STAGE(PG8_SA(0, 1), a2 + hstep, voffA);
;       PG8_WAIT_L(8); PG8_BAR; PG8_WAIT_L(0); PG8_MMA(0, 0, At, B0); PG8_BAR; PG8_SCHED;
;       PG8_LDB(B1, 1, 1); PG8_STAGE(PG8_SB(1, 0), b3, voffB);
;       PG8_BAR; PG8_WAIT_L(0); PG8_MMA(0, 1, At, B1); PG8_BAR;
	s_add_u32 s80, s0, 0x40000
	s_addc_u32 s81, s1, 0
	s_mov_b32 m0, s14
	v_lshl_add_u64 v[140:141], s[80:81], 0, v[0:1]
	global_load_lds_dwordx4 v[140:141], off
	v_lshl_add_u64 v[140:141], s[80:81], 0, v[130:131]
	s_mov_b32 m0, s15
	s_nop 0
	global_load_lds_dwordx4 v[140:141], off
	s_waitcnt vmcnt(6)
	s_barrier
	v_mfma_f32_16x16x32_bf16 v[54:57], v[198:201], v[166:169], v[54:57]
	v_mfma_f32_16x16x32_bf16 v[66:69], v[206:209], v[166:169], v[66:69]
	v_mfma_f32_16x16x32_bf16 v[94:97], v[198:201], v[174:177], v[94:97]
	v_mfma_f32_16x16x32_bf16 v[106:109], v[206:209], v[174:177], v[106:109]
	v_mfma_f32_16x16x32_bf16 v[70:73], v[198:201], v[182:185], v[70:73]
	v_mfma_f32_16x16x32_bf16 v[78:81], v[206:209], v[182:185], v[78:81]
	v_mfma_f32_16x16x32_bf16 v[26:29], v[198:201], v[190:193], v[26:29]
	v_mfma_f32_16x16x32_bf16 v[34:37], v[206:209], v[190:193], v[34:37]
	v_mfma_f32_16x16x32_bf16 v[54:57], v[202:205], v[170:173], v[54:57]
	v_mfma_f32_16x16x32_bf16 v[66:69], v[210:213], v[170:173], v[66:69]
	v_mfma_f32_16x16x32_bf16 v[94:97], v[202:205], v[178:181], v[94:97]
	v_mfma_f32_16x16x32_bf16 v[106:109], v[210:213], v[178:181], v[106:109]
	v_mfma_f32_16x16x32_bf16 v[70:73], v[202:205], v[186:189], v[70:73]
	v_mfma_f32_16x16x32_bf16 v[78:81], v[210:213], v[186:189], v[78:81]
	v_mfma_f32_16x16x32_bf16 v[26:29], v[202:205], v[194:197], v[26:29]
	v_mfma_f32_16x16x32_bf16 v[34:37], v[210:213], v[194:197], v[34:37]
	v_or_b32_e32 v140, 0x18000, v146
	v_add_u32_e32 v148, 0x18400, v146
	v_add_u32_e32 v152, 0x18800, v146
	v_add_u32_e32 v156, 0x18c00, v146
	s_barrier
	ds_read_b128 v[140:143], v140
	ds_read_b128 v[148:151], v148
	ds_read_b128 v[152:155], v152
	ds_read_b128 v[156:159], v156
	s_add_u32 s30, s30, 0x40000
	s_addc_u32 s31, s31, 0
	s_mov_b32 m0, s16
	v_lshl_add_u64 v[198:199], s[30:31], 0, v[134:135]
	ds_read_b128 v[166:169], v145 offset:32768
	ds_read_b128 v[170:173], v145 offset:33792
	ds_read_b128 v[174:177], v145 offset:34816
	ds_read_b128 v[178:181], v145 offset:35840
	ds_read_b128 v[182:185], v145 offset:36864
	ds_read_b128 v[186:189], v145 offset:37888
	ds_read_b128 v[190:193], v145 offset:38912
	ds_read_b128 v[194:197], v145 offset:39936
	global_load_lds_dwordx4 v[198:199], off
	v_lshl_add_u64 v[198:199], s[30:31], 0, v[132:133]
	s_mov_b32 m0, s18
	s_nop 0
	global_load_lds_dwordx4 v[198:199], off
	s_waitcnt lgkmcnt(8)
	s_barrier
	s_waitcnt lgkmcnt(0)
	s_waitcnt lgkmcnt(0)
	v_mfma_f32_16x16x32_bf16 v[118:121], v[140:143], v[166:169], v[118:121]
	v_mfma_f32_16x16x32_bf16 v[110:113], v[152:155], v[166:169], v[110:113]
	v_mfma_f32_16x16x32_bf16 v[90:93], v[140:143], v[174:177], v[90:93]
	v_mfma_f32_16x16x32_bf16 v[82:85], v[152:155], v[174:177], v[82:85]
	v_mfma_f32_16x16x32_bf16 v[62:65], v[140:143], v[182:185], v[62:65]
	v_mfma_f32_16x16x32_bf16 v[50:53], v[152:155], v[182:185], v[50:53]
	v_mfma_f32_16x16x32_bf16 v[42:45], v[140:143], v[190:193], v[42:45]
	v_mfma_f32_16x16x32_bf16 v[22:25], v[152:155], v[190:193], v[22:25]
	v_mfma_f32_16x16x32_bf16 v[118:121], v[148:151], v[170:173], v[118:121]
	v_mfma_f32_16x16x32_bf16 v[110:113], v[156:159], v[170:173], v[110:113]
	v_mfma_f32_16x16x32_bf16 v[90:93], v[148:151], v[178:181], v[90:93]
	v_mfma_f32_16x16x32_bf16 v[82:85], v[156:159], v[178:181], v[82:85]
	v_mfma_f32_16x16x32_bf16 v[62:65], v[148:151], v[186:189], v[62:65]
	v_mfma_f32_16x16x32_bf16 v[50:53], v[156:159], v[186:189], v[50:53]
	v_mfma_f32_16x16x32_bf16 v[42:45], v[148:151], v[194:197], v[42:45]
	v_mfma_f32_16x16x32_bf16 v[22:25], v[156:159], v[194:197], v[22:25]
	s_barrier
	v_or_b32_e32 v163, 0x1c000, v146
	s_mov_b32 m0, s8
	v_add_u32_e32 v165, 0x1c400, v146
	ds_read_b128 v[198:201], v163
	ds_read_b128 v[202:205], v165
	v_add_u32_e32 v163, 0x1c800, v146
	v_lshl_add_u64 v[160:161], v[160:161], 0, s[10:11]
	v_add_u32_e32 v165, 0x1cc00, v146
	ds_read_b128 v[206:209], v163
	ds_read_b128 v[210:213], v165
	global_load_lds_dwordx4 v[160:161], off
	v_lshl_add_u64 v[160:161], v[214:215], 0, s[10:11]
	s_mov_b32 m0, s9
	s_nop 0
	global_load_lds_dwordx4 v[160:161], off
	s_barrier
	s_waitcnt lgkmcnt(0)
	s_waitcnt lgkmcnt(0)
	v_mfma_f32_16x16x32_bf16 v[122:125], v[198:201], v[166:169], v[122:125]
	v_mfma_f32_16x16x32_bf16 v[126:129], v[206:209], v[166:169], v[126:129]
	v_mfma_f32_16x16x32_bf16 v[102:105], v[198:201], v[174:177], v[102:105]
	v_mfma_f32_16x16x32_bf16 v[114:117], v[206:209], v[174:177], v[114:117]
	v_mfma_f32_16x16x32_bf16 v[86:89], v[198:201], v[182:185], v[86:89]
	v_mfma_f32_16x16x32_bf16 v[98:101], v[206:209], v[182:185], v[98:101]
	v_mfma_f32_16x16x32_bf16 v[58:61], v[198:201], v[190:193], v[58:61]
	v_mfma_f32_16x16x32_bf16 v[74:77], v[206:209], v[190:193], v[74:77]
	v_mfma_f32_16x16x32_bf16 v[122:125], v[202:205], v[170:173], v[122:125]
	v_mfma_f32_16x16x32_bf16 v[126:129], v[210:213], v[170:173], v[126:129]
	v_mfma_f32_16x16x32_bf16 v[102:105], v[202:205], v[178:181], v[102:105]
	v_mfma_f32_16x16x32_bf16 v[114:117], v[210:213], v[178:181], v[114:117]
	v_mfma_f32_16x16x32_bf16 v[86:89], v[202:205], v[186:189], v[86:89]
	v_mfma_f32_16x16x32_bf16 v[98:101], v[210:213], v[186:189], v[98:101]
	v_mfma_f32_16x16x32_bf16 v[58:61], v[202:205], v[194:197], v[58:61]
	v_mfma_f32_16x16x32_bf16 v[74:77], v[210:213], v[194:197], v[74:77]
	s_mov_b32 m0, s19
	v_lshl_add_u64 v[160:161], v[216:217], 0, s[10:11]
	s_barrier
; DI bf16_t f2bf(float x) { unsigned u = __float_as_uint(x); u += 0x7fffu + ((u >> 16) & 1u); return (bf16_t)(u >> 16); }
; DI unsigned pack2(float lo, float hi) { f32x2_t v = {lo, hi}; return __builtin_bit_cast(unsigned, __builtin_convertvector(v, bf16x2_t)); }
; #define PG8_STAGE(bufoff, gbase, voff) do { _Pragma("unroll") for (int _i = 0; _i < 2; ++_i) \
;     __builtin_amdgcn_global_load_lds((const unsigned*)((const char*)(gbase) + (voff)[_i]), (PG8_LAS unsigned*)(lds + (bufoff) + ldsw + _i * 8192), 16, 0, 0); } while (0)
; #define PG8_LDA(dst, b, h) do { _Pragma("unroll") for (int m = 0; m < 4; ++m) _Pragma("unroll") for (int k = 0; k < 2; ++k) dst[m][k] = *(const PG8_LAS bf16x8*)(lds + PG8_SA(b, h) + aoff + m * 2048 + k * 1024); } while (0)
; #define PG8_WAIT_V(n) asm volatile("s_waitcnt vmcnt(" #n ")" ::: "memory")
; #define PG8_WAIT_L(n) asm volatile("s_waitcnt lgkmcnt(" #n ")" ::: "memory")
; #define PG8_BAR __builtin_amdgcn_s_barrier()
; #define PG8_SCHED __builtin_amdgcn_sched_barrier(0)
;   DI void operator()(const f32x4 (&acc)[2][2][4][2], const Unit& u, int wr, int wc, int fr, int fq, const PG8_LAS float*) const {
;     ...
;       for (int m = 0; m < 4; ++m) { const int row = row0 + ai * HALF + m * 16; bf16_t* rowp = dst + (size_t)row * DM + col0; float ss = 0.f;
; #pragma unroll
;         for (int bj = 0; bj < 2; ++bj) { const f32x4 v0 = acc[ai][bj][m][0] * coef, v1 = acc[ai][bj][m][1] * coef;
;           ss += v0[0] * v0[0] + v0[1] * v0[1] + v0[2] * v0[2] + v0[3] * v0[3] + v1[0] * v1[0] + v1[1] * v1[1] + v1[2] * v1[2] + v1[3] * v1[3];
;           u32x4 w; w.x = pack2(v0[0], v0[1]); w.y = pack2(v0[2], v0[3]); w.z = pack2(v1[0], v1[1]); w.w = pack2(v1[2], v1[3]);
;           *(u32x4*)(rowp + bj * HALF) = w; }
;         ss += __shfl_xor(ss, 16); ss += __shfl_xor(ss, 32);
;         if (fq == 0) ssq[(size_t)row * 16 + u.pn * 4 + wc] = f2bf(ss); }
; template <class Epi>
; DI void gemm_phase(const bf16_t* __restrict__ gA, const bf16_t* __restrict__ gBt, int M, int N, int K, const Epi& E, char* lds_generic) {
;     ...
;       PG8_LDA(At, 1, 1); PG8_STAGE(PG8_SA(1, 0), a3, voffA);
;       PG8_BAR; PG8_WAIT_L(0); PG8_MMA(1, 0, At, B0); PG8_BAR; PG8_SCHED;
;       PG8_STAGE(PG8_SB(1, 1), b3 + hstep, voffB);
;       PG8_WAIT_V(6); PG8_BAR; PG8_MMA(1, 1, At, B1); PG8_BAR;
	ds_read_b128 v[166:169], v145 offset:49152
	ds_read_b128 v[170:173], v145 offset:50176
	ds_read_b128 v[174:177], v145 offset:51200
	ds_read_b128 v[178:181], v145 offset:52224
	ds_read_b128 v[182:185], v145 offset:53248
	ds_read_b128 v[186:189], v145 offset:54272
	ds_read_b128 v[190:193], v145 offset:55296
	ds_read_b128 v[194:197], v145 offset:56320
	global_load_lds_dwordx4 v[160:161], off
	v_lshl_add_u64 v[160:161], v[218:219], 0, s[10:11]
	s_mov_b32 m0, s33
	s_nop 0
	global_load_lds_dwordx4 v[160:161], off
	s_barrier
	s_waitcnt lgkmcnt(0)
	s_waitcnt lgkmcnt(0)
	v_mfma_f32_16x16x32_bf16 v[38:41], v[140:143], v[166:169], v[38:41]
	v_mfma_f32_16x16x32_bf16 v[18:21], v[152:155], v[166:169], v[18:21]
	v_mfma_f32_16x16x32_bf16 v[10:13], v[140:143], v[174:177], v[10:13]
	v_mfma_f32_16x16x32_bf16 v[2:5], v[152:155], v[174:177], v[2:5]
	v_mfma_f32_16x16x32_bf16 v[46:49], v[140:143], v[182:185], v[46:49]
	v_mfma_f32_16x16x32_bf16 v[30:33], v[152:155], v[182:185], v[30:33]
	v_mfma_f32_16x16x32_bf16 v[14:17], v[140:143], v[190:193], v[14:17]
	v_mfma_f32_16x16x32_bf16 v[6:9], v[152:155], v[190:193], v[6:9]
	v_mfma_f32_16x16x32_bf16 v[38:41], v[148:151], v[170:173], v[38:41]
	v_mfma_f32_16x16x32_bf16 v[18:21], v[156:159], v[170:173], v[18:21]
	v_mfma_f32_16x16x32_bf16 v[10:13], v[148:151], v[178:181], v[10:13]
	v_mfma_f32_16x16x32_bf16 v[2:5], v[156:159], v[178:181], v[2:5]
	v_mfma_f32_16x16x32_bf16 v[46:49], v[148:151], v[186:189], v[46:49]
	v_mfma_f32_16x16x32_bf16 v[30:33], v[156:159], v[186:189], v[30:33]
	v_mfma_f32_16x16x32_bf16 v[14:17], v[148:151], v[194:197], v[14:17]
	v_mfma_f32_16x16x32_bf16 v[6:9], v[156:159], v[194:197], v[6:9]
	s_barrier
	s_add_u32 s0, s0, 0x40080
	s_addc_u32 s1, s1, 0
	s_mov_b32 m0, s35
	v_lshl_add_u64 v[140:141], s[0:1], 0, v[0:1]
	global_load_lds_dwordx4 v[140:141], off
	v_lshl_add_u64 v[140:141], s[0:1], 0, v[130:131]
	s_mov_b32 m0, s42
	s_nop 0
	global_load_lds_dwordx4 v[140:141], off
	s_waitcnt vmcnt(6)
	s_barrier
	v_mfma_f32_16x16x32_bf16 v[54:57], v[198:201], v[166:169], v[54:57]
	v_mfma_f32_16x16x32_bf16 v[66:69], v[206:209], v[166:169], v[66:69]
	v_mfma_f32_16x16x32_bf16 v[94:97], v[198:201], v[174:177], v[94:97]
	v_mfma_f32_16x16x32_bf16 v[106:109], v[206:209], v[174:177], v[106:109]
	v_mfma_f32_16x16x32_bf16 v[70:73], v[198:201], v[182:185], v[70:73]
	v_mfma_f32_16x16x32_bf16 v[78:81], v[206:209], v[182:185], v[78:81]
	v_mfma_f32_16x16x32_bf16 v[26:29], v[198:201], v[190:193], v[26:29]
	v_mfma_f32_16x16x32_bf16 v[34:37], v[206:209], v[190:193], v[34:37]
	v_mfma_f32_16x16x32_bf16 v[54:57], v[202:205], v[170:173], v[54:57]
	v_mfma_f32_16x16x32_bf16 v[66:69], v[210:213], v[170:173], v[66:69]
	v_mfma_f32_16x16x32_bf16 v[94:97], v[202:205], v[178:181], v[94:97]
	v_mfma_f32_16x16x32_bf16 v[106:109], v[210:213], v[178:181], v[106:109]
	v_mfma_f32_16x16x32_bf16 v[70:73], v[202:205], v[186:189], v[70:73]
	v_mfma_f32_16x16x32_bf16 v[78:81], v[210:213], v[186:189], v[78:81]
	v_mfma_f32_16x16x32_bf16 v[26:29], v[202:205], v[194:197], v[26:29]
	v_mfma_f32_16x16x32_bf16 v[34:37], v[210:213], v[194:197], v[34:37]
	s_add_i32 s60, s60, 2
	s_add_u32 s28, s28, 0x100
	s_addc_u32 s29, s29, 0
	s_add_u32 s58, s58, 0x100
	s_addc_u32 s59, s59, 0
	s_cmp_gt_u32 s60, 13
	s_barrier
	s_cbranch_scc0 .LBB0_511
	v_mul_f32_e32 v152, v119, v119
	v_fmac_f32_e32 v152, v118, v118
	v_fmac_f32_e32 v152, v120, v120
	v_cvt_pk_bf16_f32 v118, v118, v119
	v_cvt_pk_bf16_f32 v119, v120, v121
	v_mul_f32_e32 v120, v123, v123
	v_fmac_f32_e32 v120, v122, v122
	v_fmac_f32_e32 v120, v124, v124
	v_fmac_f32_e32 v152, v121, v121
	v_fmac_f32_e32 v120, v125, v125
	v_fmac_f32_e32 v152, v110, v110
	v_fmac_f32_e32 v120, v126, v126
	v_xor_b32_e32 v143, 16, v223
	v_fmac_f32_e32 v152, v111, v111
	v_fmac_f32_e32 v120, v127, v127
	v_cmp_lt_i32_e64 s[0:1], v143, v225
	v_fmac_f32_e32 v152, v112, v112
	v_fmac_f32_e32 v120, v128, v128
	v_cndmask_b32_e64 v143, v223, v143, s[0:1]
	v_fmac_f32_e32 v152, v113, v113
	v_fmac_f32_e32 v120, v129, v129
	v_lshlrev_b32_e32 v149, 2, v143
	v_add_f32_e32 v152, v152, v120
	ds_bpermute_b32 v153, v149, v152
	v_xor_b32_e32 v143, 32, v223
	v_cmp_lt_i32_e64 s[0:1], v143, v225
	v_lshl_add_u32 v142, s21, 8, v144
	v_cvt_pk_bf16_f32 v120, v110, v111
	v_cndmask_b32_e64 v143, v223, v143, s[0:1]
	v_lshlrev_b32_e32 v148, 2, v143
	s_waitcnt lgkmcnt(0)
	v_add_f32_e32 v110, v152, v153
	v_ashrrev_i32_e32 v143, 31, v142
	ds_bpermute_b32 v111, v148, v110
	v_lshl_or_b32 v140, s20, 8, v147
	v_lshlrev_b64 v[150:151], 11, v[142:143]
	v_ashrrev_i32_e32 v141, 31, v140
	v_lshl_add_u64 v[150:151], s[92:93], 0, v[150:151]
	s_lshl_b32 s0, s20, 2
	v_lshl_add_u64 v[150:151], v[140:141], 1, v[150:151]
	v_cvt_pk_bf16_f32 v121, v112, v113
	s_ashr_i32 s1, s0, 31
	global_store_dwordx4 v[150:151], v[118:121], off
	s_nop 1
	v_cvt_pk_bf16_f32 v118, v122, v123
	v_cvt_pk_bf16_f32 v119, v124, v125
	v_cvt_pk_bf16_f32 v120, v126, v127
	v_cvt_pk_bf16_f32 v121, v128, v129
	global_store_dwordx4 v[150:151], v[118:121], off offset:256
	s_and_saveexec_b64 s[28:29], s[36:37]
	s_cbranch_execz .LBB0_514
	s_waitcnt lgkmcnt(0)
	v_add_f32_e32 v110, v110, v111
	v_bfe_u32 v111, v110, 16, 1
	v_add3_u32 v112, v110, v111, s63
	v_lshlrev_b64 v[110:111], 5, v[142:143]
	v_lshl_add_u64 v[110:111], s[70:71], 0, v[110:111]
	v_lshl_add_u64 v[110:111], s[0:1], 1, v[110:111]
	s_lshl_b32 s76, s5, 1
	v_lshl_add_u64 v[110:111], v[110:111], 0, s[76:77]
	global_store_short_d16_hi v[110:111], v112, off

; #define PG8_STAGE(bufoff, gbase, voff) do { _Pragma("unroll") for (int _i = 0; _i < 2; ++_i) \
;     __builtin_amdgcn_global_load_lds((const unsigned*)((const char*)(gbase) + (voff)[_i]), (PG8_LAS unsigned*)(lds + (bufoff) + ldsw + _i * 8192), 16, 0, 0); } while (0)
; #define PG8_LDA(dst, b, h) do { _Pragma("unroll") for (int m = 0; m < 4; ++m) _Pragma("unroll") for (int k = 0; k < 2; ++k) dst[m][k] = *(const PG8_LAS bf16x8*)(lds + PG8_SA(b, h) + aoff + m * 2048 + k * 1024); } while (0)
; #define PG8_LDB(dst, b, h) do { _Pragma("unroll") for (int n = 0; n < 2; ++n) _Pragma("unroll") for (int k = 0; k < 2; ++k) dst[n][k] = *(const PG8_LAS bf16x8*)(lds + PG8_SB(b, h) + boff + n * 2048 + k * 1024); } while (0)
; #define PG8_MMA(ai, bj, At, Bt) do { __builtin_amdgcn_s_setprio(1); _Pragma("unroll") for (int m = 0; m < 4; ++m) _Pragma("unroll") for (int n = 0; n < 2; ++n) _Pragma("unroll") for (int k = 0; k < 2; ++k) \
;     acc[ai][bj][m][n] = __builtin_amdgcn_mfma_f32_16x16x32_bf16(Bt[n][k], At[m][k], acc[ai][bj][m][n], 0, 0, 0); __builtin_amdgcn_s_setprio(0); } while (0)
; #define PG8_WAIT_L(n) asm volatile("s_waitcnt lgkmcnt(" #n ")" ::: "memory")
; #define PG8_BAR __builtin_amdgcn_s_barrier()
; template <class Epi>
; DI void gemm_phase(const bf16_t* __restrict__ gA, const bf16_t* __restrict__ gBt, int M, int N, int K, const Epi& E, char* lds_generic) {
;     ...
;     const bool has_next = S.next(ui + 1, nxt);
;     const char* nA = has_next ? (const char*)gA + (size_t)nxt.pm * tstep : cA; const char* nB = has_next ? (const char*)gBt + (size_t)nxt.pn * tstep : cB;
;     for (int t = 0; t < nt; t += 2) {
;       const bool last = (t == nt - 2);
;       const char* a1 = cA + (size_t)(t + 1) * kstep;
;       const char* a2 = last ? nA : cA + (size_t)(t + 2) * kstep; const char* b2 = last ? nB : cB + (size_t)(t + 2) * kstep;
;       const char* a3 = a2 + kstep; const char* b3 = b2 + kstep;
;       PG8_LDB(B0, 0, 0); PG8_SCHED; PG8_LDA(At, 0, 0); PG8_STAGE(PG8_SA(1, 1), a1 + hstep, voffA);
;       PG8_WAIT_L(8); PG8_BAR; PG8_WAIT_L(0); PG8_MMA(0, 0, At, B0); PG8_BAR; PG8_SCHED;
;       PG8_LDB(B1, 0, 1); PG8_STAGE(PG8_SB(0, 0), b2, voffB);
;       PG8_BAR; PG8_WAIT_L(0); PG8_MMA(0, 1, At, B1); PG8_BAR;
;       PG8_LDA(At, 0, 1); PG8_STAGE(PG8_SA(0, 0), a2, voffA);
;       PG8_BAR; PG8_WAIT_L(0); PG8_MMA(1, 0, At, B0); PG8_BAR; PG8_SCHED;
.LBB0_604:
	s_ashr_i32 s87, s86, 31
	s_lshl_b64 s[20:21], s[86:87], 19
	s_add_u32 s88, s82, s20
	s_addc_u32 s89, s83, s21
	s_and_b64 s[20:21], s[38:39], exec
	s_cselect_b32 s20, s89, s29
	s_cselect_b32 s21, s88, s28
	s_ashr_i32 s27, s26, 31
	s_lshl_b64 s[22:23], s[26:27], 19
	s_add_u32 s90, s16, s22
	s_addc_u32 s91, s4, s23
	s_and_b64 s[22:23], s[38:39], exec
	s_cselect_b32 s27, s91, s31
	s_cselect_b32 s42, s90, s30
	s_add_u32 vcc_lo, s28, 0x40080
	s_addc_u32 vcc_hi, s29, 0
	s_add_u32 s87, s30, 0x100
	s_addc_u32 s22, s31, 0
	s_mov_b32 s23, -2
	v_or_b32_e32 v50, 0x10000, v155
	v_add_u32_e32 v146, 0x10400, v155
	v_add_u32_e32 v158, 0x10800, v155
	ds_read_b128 v[50:53], v50
	ds_read_b128 v[146:149], v146
	v_add_u32_e32 v163, 0x10c00, v155
	ds_read_b128 v[158:161], v158
	ds_read_b128 v[166:169], v163
	s_add_u32 s24, vcc_lo, 0xfffc0080
	s_addc_u32 s25, vcc_hi, -1
	s_cmp_eq_u32 s23, 12
	s_cselect_b32 s31, s20, s25
	s_cselect_b32 s30, s21, s24
	s_cselect_b32 s29, s27, s22
	s_cselect_b32 s28, s42, s87
	v_lshl_add_u64 v[202:203], vcc, 0, v[142:143]
	s_add_i32 m0, s72, 0xc000
	ds_read_b128 v[170:173], v154
	ds_read_b128 v[174:177], v154 offset:1024
	ds_read_b128 v[178:181], v154 offset:2048
	ds_read_b128 v[182:185], v154 offset:3072
	ds_read_b128 v[186:189], v154 offset:4096
	ds_read_b128 v[190:193], v154 offset:5120
	ds_read_b128 v[194:197], v154 offset:6144
	ds_read_b128 v[198:201], v154 offset:7168
	global_load_lds_dwordx4 v[202:203], off
	v_lshl_add_u64 v[202:203], vcc, 0, v[144:145]
	s_add_i32 m0, s72, 0xe000
	s_nop 0
	global_load_lds_dwordx4 v[202:203], off
	s_waitcnt lgkmcnt(8)
	s_barrier
	s_waitcnt lgkmcnt(0)
	s_waitcnt lgkmcnt(0)
	v_mfma_f32_16x16x32_bf16 v[130:133], v[50:53], v[170:173], 0
	v_mfma_f32_16x16x32_bf16 v[122:125], v[158:161], v[170:173], 0
	v_mfma_f32_16x16x32_bf16 v[114:117], v[50:53], v[178:181], 0
	v_mfma_f32_16x16x32_bf16 v[106:109], v[158:161], v[178:181], 0
	v_mfma_f32_16x16x32_bf16 v[98:101], v[50:53], v[186:189], 0
	v_mfma_f32_16x16x32_bf16 v[90:93], v[158:161], v[186:189], 0
	v_mfma_f32_16x16x32_bf16 v[82:85], v[50:53], v[194:197], 0
	v_mfma_f32_16x16x32_bf16 v[74:77], v[158:161], v[194:197], 0
	v_mfma_f32_16x16x32_bf16 v[130:133], v[146:149], v[174:177], v[130:133]
	v_mfma_f32_16x16x32_bf16 v[122:125], v[166:169], v[174:177], v[122:125]
	v_mfma_f32_16x16x32_bf16 v[114:117], v[146:149], v[182:185], v[114:117]
	v_mfma_f32_16x16x32_bf16 v[106:109], v[166:169], v[182:185], v[106:109]
	v_mfma_f32_16x16x32_bf16 v[98:101], v[146:149], v[190:193], v[98:101]
	v_mfma_f32_16x16x32_bf16 v[90:93], v[166:169], v[190:193], v[90:93]
	v_mfma_f32_16x16x32_bf16 v[82:85], v[146:149], v[198:201], v[82:85]
	v_mfma_f32_16x16x32_bf16 v[74:77], v[166:169], v[198:201], v[74:77]
	s_barrier
	v_or_b32_e32 v163, 0x14000, v155
	s_mov_b32 m0, s14
	v_add_u32_e32 v165, 0x14400, v155
	ds_read_b128 v[202:205], v163
	ds_read_b128 v[206:209], v165
	v_add_u32_e32 v163, 0x14800, v155
	v_lshl_add_u64 v[218:219], s[28:29], 0, v[0:1]
	v_add_u32_e32 v165, 0x14c00, v155
	ds_read_b128 v[210:213], v163
	ds_read_b128 v[214:217], v165
	global_load_lds_dwordx4 v[218:219], off
	v_lshl_add_u64 v[220:221], s[28:29], 0, v[138:139]
	s_mov_b32 m0, s15
	s_nop 0
	global_load_lds_dwordx4 v[220:221], off
	s_barrier
	s_waitcnt lgkmcnt(0)
	s_waitcnt lgkmcnt(0)
	v_mfma_f32_16x16x32_bf16 v[126:129], v[202:205], v[170:173], 0
	v_mfma_f32_16x16x32_bf16 v[118:121], v[210:213], v[170:173], 0
	v_mfma_f32_16x16x32_bf16 v[110:113], v[202:205], v[178:181], 0
	v_mfma_f32_16x16x32_bf16 v[102:105], v[210:213], v[178:181], 0
	v_mfma_f32_16x16x32_bf16 v[94:97], v[202:205], v[186:189], 0
	v_mfma_f32_16x16x32_bf16 v[86:89], v[210:213], v[186:189], 0
	v_mfma_f32_16x16x32_bf16 v[78:81], v[202:205], v[194:197], 0
	v_mfma_f32_16x16x32_bf16 v[70:73], v[210:213], v[194:197], 0
	v_mfma_f32_16x16x32_bf16 v[126:129], v[206:209], v[174:177], v[126:129]
	v_mfma_f32_16x16x32_bf16 v[118:121], v[214:217], v[174:177], v[118:121]
	v_mfma_f32_16x16x32_bf16 v[110:113], v[206:209], v[182:185], v[110:113]
	v_mfma_f32_16x16x32_bf16 v[102:105], v[214:217], v[182:185], v[102:105]
	v_mfma_f32_16x16x32_bf16 v[94:97], v[206:209], v[190:193], v[94:97]
	v_mfma_f32_16x16x32_bf16 v[86:89], v[214:217], v[190:193], v[86:89]
	v_mfma_f32_16x16x32_bf16 v[78:81], v[206:209], v[198:201], v[78:81]
	v_mfma_f32_16x16x32_bf16 v[70:73], v[214:217], v[198:201], v[70:73]
	s_mov_b32 m0, s72
	v_lshl_add_u64 v[226:227], s[30:31], 0, v[134:135]
	s_barrier
	ds_read_b128 v[170:173], v154 offset:16384
	ds_read_b128 v[174:177], v154 offset:17408
	ds_read_b128 v[178:181], v154 offset:18432
	ds_read_b128 v[182:185], v154 offset:19456
	ds_read_b128 v[186:189], v154 offset:20480
	ds_read_b128 v[190:193], v154 offset:21504
	ds_read_b128 v[194:197], v154 offset:22528
	ds_read_b128 v[198:201], v154 offset:23552
	global_load_lds_dwordx4 v[226:227], off
	v_lshl_add_u64 v[228:229], s[30:31], 0, v[136:137]
	s_mov_b32 m0, s58
	s_nop 0
	global_load_lds_dwordx4 v[228:229], off
	s_barrier
	s_waitcnt lgkmcnt(0)
	s_waitcnt lgkmcnt(0)
	v_mfma_f32_16x16x32_bf16 v[66:69], v[50:53], v[170:173], 0
	v_mfma_f32_16x16x32_bf16 v[58:61], v[158:161], v[170:173], 0
	v_mfma_f32_16x16x32_bf16 v[46:49], v[50:53], v[178:181], 0
	v_mfma_f32_16x16x32_bf16 v[38:41], v[158:161], v[178:181], 0
	v_mfma_f32_16x16x32_bf16 v[30:33], v[50:53], v[186:189], 0
	v_mfma_f32_16x16x32_bf16 v[22:25], v[158:161], v[186:189], 0
	v_mfma_f32_16x16x32_bf16 v[14:17], v[50:53], v[194:197], 0
	v_mfma_f32_16x16x32_bf16 v[6:9], v[158:161], v[194:197], 0
	v_mfma_f32_16x16x32_bf16 v[66:69], v[146:149], v[174:177], v[66:69]
	v_mfma_f32_16x16x32_bf16 v[58:61], v[166:169], v[174:177], v[58:61]
	v_mfma_f32_16x16x32_bf16 v[46:49], v[146:149], v[182:185], v[46:49]
	v_mfma_f32_16x16x32_bf16 v[38:41], v[166:169], v[182:185], v[38:41]
	v_mfma_f32_16x16x32_bf16 v[30:33], v[146:149], v[190:193], v[30:33]
	v_mfma_f32_16x16x32_bf16 v[22:25], v[166:169], v[190:193], v[22:25]
	v_mfma_f32_16x16x32_bf16 v[14:17], v[146:149], v[198:201], v[14:17]
	v_mfma_f32_16x16x32_bf16 v[6:9], v[166:169], v[198:201], v[6:9]
	s_barrier
; #define PG8_STAGE(bufoff, gbase, voff) do { _Pragma("unroll") for (int _i = 0; _i < 2; ++_i) \
;     __builtin_amdgcn_global_load_lds((const unsigned*)((const char*)(gbase) + (voff)[_i]), (PG8_LAS unsigned*)(lds + (bufoff) + ldsw + _i * 8192), 16, 0, 0); } while (0)
; #define PG8_LDA(dst, b, h) do { _Pragma("unroll") for (int m = 0; m < 4; ++m) _Pragma("unroll") for (int k = 0; k < 2; ++k) dst[m][k] = *(const PG8_LAS bf16x8*)(lds + PG8_SA(b, h) + aoff + m * 2048 + k * 1024); } while (0)
; #define PG8_LDB(dst, b, h) do { _Pragma("unroll") for (int n = 0; n < 2; ++n) _Pragma("unroll") for (int k = 0; k < 2; ++k) dst[n][k] = *(const PG8_LAS bf16x8*)(lds + PG8_SB(b, h) + boff + n * 2048 + k * 1024); } while (0)
; #define PG8_WAIT_V(n) asm volatile("s_waitcnt vmcnt(" #n ")" ::: "memory")
; #define PG8_WAIT_L(n) asm volatile("s_waitcnt lgkmcnt(" #n ")" ::: "memory")
; #define PG8_BAR __builtin_amdgcn_s_barrier()
; #define PG8_SCHED __builtin_amdgcn_sched_barrier(0)
; template <class Epi>
; DI void gemm_phase(const bf16_t* __restrict__ gA, const bf16_t* __restrict__ gBt, int M, int N, int K, const Epi& E, char* lds_generic) {
;     ...
;     for (int t = 0; t < nt; t += 2) {
;       const bool last = (t == nt - 2);
;       const char* a1 = cA + (size_t)(t + 1) * kstep;
;       const char* a2 = last ? nA : cA + (size_t)(t + 2) * kstep; const char* b2 = last ? nB : cB + (size_t)(t + 2) * kstep;
;       const char* a3 = a2 + kstep; const char* b3 = b2 + kstep;
;       PG8_LDB(B0, 0, 0); PG8_SCHED; PG8_LDA(At, 0, 0); PG8_STAGE(PG8_SA(1, 1), a1 + hstep, voffA);
;       PG8_WAIT_L(8); PG8_BAR; PG8_WAIT_L(0); PG8_MMA(0, 0, At, B0); PG8_BAR; PG8_SCHED;
;       PG8_LDB(B1, 0, 1); PG8_STAGE(PG8_SB(0, 0), b2, voffB);
;       PG8_BAR; PG8_WAIT_L(0); PG8_MMA(0, 1, At, B1); PG8_BAR;
;       PG8_LDA(At, 0, 1); PG8_STAGE(PG8_SA(0, 0), a2, voffA);
;       PG8_BAR; PG8_WAIT_L(0); PG8_MMA(1, 0, At, B0); PG8_BAR; PG8_SCHED;
;       PG8_STAGE(PG8_SB(0, 1), b2 + hstep, voffB);
;       PG8_WAIT_V(6); PG8_BAR; PG8_MMA(1, 1, At, B1); PG8_BAR;
;       PG8_LDB(B0, 1, 0); PG8_SCHED; PG8_LDA(At, 1, 0); PG8_STAGE(PG8_SA(0, 1), a2 + hstep, voffA);
;       PG8_WAIT_L(8); PG8_BAR; PG8_WAIT_L(0); PG8_MMA(0, 0, At, B0); PG8_BAR; PG8_SCHED;
;       PG8_LDB(B1, 1, 1); PG8_STAGE(PG8_SB(1, 0), b3, voffB);
;       PG8_BAR; PG8_WAIT_L(0); PG8_MMA(0, 1, At, B1); PG8_BAR;
	s_add_u32 s24, s28, 0x40000
	s_addc_u32 s25, s29, 0
	s_mov_b32 m0, s59
	v_lshl_add_u64 v[50:51], s[24:25], 0, v[0:1]
	global_load_lds_dwordx4 v[50:51], off
	v_lshl_add_u64 v[50:51], s[24:25], 0, v[138:139]
	s_mov_b32 m0, s62
	s_nop 0
	global_load_lds_dwordx4 v[50:51], off
	s_waitcnt vmcnt(6)
	s_barrier
	v_mfma_f32_16x16x32_bf16 v[54:57], v[210:213], v[170:173], 0
	v_mfma_f32_16x16x32_bf16 v[42:45], v[202:205], v[178:181], 0
	v_mfma_f32_16x16x32_bf16 v[34:37], v[210:213], v[178:181], 0
	v_mfma_f32_16x16x32_bf16 v[26:29], v[202:205], v[186:189], 0
	v_mfma_f32_16x16x32_bf16 v[18:21], v[210:213], v[186:189], 0
	v_mfma_f32_16x16x32_bf16 v[10:13], v[202:205], v[194:197], 0
	v_mfma_f32_16x16x32_bf16 v[2:5], v[210:213], v[194:197], 0
	v_mfma_f32_16x16x32_bf16 v[50:53], v[202:205], v[170:173], 0
	v_mfma_f32_16x16x32_bf16 v[54:57], v[214:217], v[174:177], v[54:57]
	v_mfma_f32_16x16x32_bf16 v[42:45], v[206:209], v[182:185], v[42:45]
	v_mfma_f32_16x16x32_bf16 v[34:37], v[214:217], v[182:185], v[34:37]
	v_mfma_f32_16x16x32_bf16 v[26:29], v[206:209], v[190:193], v[26:29]
	v_mfma_f32_16x16x32_bf16 v[18:21], v[214:217], v[190:193], v[18:21]
	v_mfma_f32_16x16x32_bf16 v[10:13], v[206:209], v[198:201], v[10:13]
	v_mfma_f32_16x16x32_bf16 v[2:5], v[214:217], v[198:201], v[2:5]
	v_mfma_f32_16x16x32_bf16 v[50:53], v[206:209], v[174:177], v[50:53]
	v_or_b32_e32 v62, 0x18000, v155
	v_add_u32_e32 v146, 0x18400, v155
	v_add_u32_e32 v158, 0x18800, v155
	s_barrier
	s_branch .Lup605_p5
.LBB0_605:
	v_or_b32_e32 v50, 0x10000, v155
	v_add_u32_e32 v146, 0x10400, v155
	v_add_u32_e32 v158, 0x10800, v155
	ds_read_b128 v[50:53], v50
	ds_read_b128 v[146:149], v146
	v_add_u32_e32 v163, 0x10c00, v155
	ds_read_b128 v[158:161], v158
	ds_read_b128 v[166:169], v163
	s_add_u32 s24, vcc_lo, 0xfffc0080
	s_addc_u32 s25, vcc_hi, -1
	s_cmp_eq_u32 s23, 12
	s_cselect_b32 s31, s20, s25
	s_cselect_b32 s30, s21, s24
	s_cselect_b32 s29, s27, s22
	s_cselect_b32 s28, s42, s87
	v_lshl_add_u64 v[202:203], vcc, 0, v[142:143]
	s_add_i32 m0, s72, 0xc000
	ds_read_b128 v[170:173], v154
	ds_read_b128 v[174:177], v154 offset:1024
	ds_read_b128 v[178:181], v154 offset:2048
	ds_read_b128 v[182:185], v154 offset:3072
	ds_read_b128 v[186:189], v154 offset:4096
	ds_read_b128 v[190:193], v154 offset:5120
	ds_read_b128 v[194:197], v154 offset:6144
	ds_read_b128 v[198:201], v154 offset:7168
	global_load_lds_dwordx4 v[202:203], off
	v_lshl_add_u64 v[202:203], vcc, 0, v[144:145]
	s_add_i32 m0, s72, 0xe000
	s_nop 0
	global_load_lds_dwordx4 v[202:203], off
	s_waitcnt lgkmcnt(8)
	s_barrier
	s_waitcnt lgkmcnt(0)
	s_waitcnt lgkmcnt(0)
	v_mfma_f32_16x16x32_bf16 v[130:133], v[50:53], v[170:173], v[130:133]
	v_mfma_f32_16x16x32_bf16 v[122:125], v[158:161], v[170:173], v[122:125]
	v_mfma_f32_16x16x32_bf16 v[114:117], v[50:53], v[178:181], v[114:117]
	v_mfma_f32_16x16x32_bf16 v[106:109], v[158:161], v[178:181], v[106:109]
	v_mfma_f32_16x16x32_bf16 v[98:101], v[50:53], v[186:189], v[98:101]
	v_mfma_f32_16x16x32_bf16 v[90:93], v[158:161], v[186:189], v[90:93]
	v_mfma_f32_16x16x32_bf16 v[82:85], v[50:53], v[194:197], v[82:85]
	v_mfma_f32_16x16x32_bf16 v[74:77], v[158:161], v[194:197], v[74:77]
	v_mfma_f32_16x16x32_bf16 v[130:133], v[146:149], v[174:177], v[130:133]
	v_mfma_f32_16x16x32_bf16 v[122:125], v[166:169], v[174:177], v[122:125]
	v_mfma_f32_16x16x32_bf16 v[114:117], v[146:149], v[182:185], v[114:117]
	v_mfma_f32_16x16x32_bf16 v[106:109], v[166:169], v[182:185], v[106:109]
	v_mfma_f32_16x16x32_bf16 v[98:101], v[146:149], v[190:193], v[98:101]
	v_mfma_f32_16x16x32_bf16 v[90:93], v[166:169], v[190:193], v[90:93]
	v_mfma_f32_16x16x32_bf16 v[82:85], v[146:149], v[198:201], v[82:85]
	v_mfma_f32_16x16x32_bf16 v[74:77], v[166:169], v[198:201], v[74:77]
	s_barrier
	v_or_b32_e32 v163, 0x14000, v155
	s_mov_b32 m0, s14
	v_add_u32_e32 v165, 0x14400, v155
	ds_read_b128 v[202:205], v163
	ds_read_b128 v[206:209], v165
	v_add_u32_e32 v163, 0x14800, v155
	v_lshl_add_u64 v[218:219], s[28:29], 0, v[0:1]
	v_add_u32_e32 v165, 0x14c00, v155
	ds_read_b128 v[210:213], v163
	ds_read_b128 v[214:217], v165
	global_load_lds_dwordx4 v[218:219], off
	v_lshl_add_u64 v[220:221], s[28:29], 0, v[138:139]
	s_mov_b32 m0, s15
	s_nop 0
	global_load_lds_dwordx4 v[220:221], off
	s_barrier
	s_waitcnt lgkmcnt(0)
	s_waitcnt lgkmcnt(0)
	v_mfma_f32_16x16x32_bf16 v[126:129], v[202:205], v[170:173], v[126:129]
	v_mfma_f32_16x16x32_bf16 v[118:121], v[210:213], v[170:173], v[118:121]
	v_mfma_f32_16x16x32_bf16 v[110:113], v[202:205], v[178:181], v[110:113]
	v_mfma_f32_16x16x32_bf16 v[102:105], v[210:213], v[178:181], v[102:105]
	v_mfma_f32_16x16x32_bf16 v[94:97], v[202:205], v[186:189], v[94:97]
	v_mfma_f32_16x16x32_bf16 v[86:89], v[210:213], v[186:189], v[86:89]
	v_mfma_f32_16x16x32_bf16 v[78:81], v[202:205], v[194:197], v[78:81]
	v_mfma_f32_16x16x32_bf16 v[70:73], v[210:213], v[194:197], v[70:73]
	v_mfma_f32_16x16x32_bf16 v[126:129], v[206:209], v[174:177], v[126:129]
	v_mfma_f32_16x16x32_bf16 v[118:121], v[214:217], v[174:177], v[118:121]
	v_mfma_f32_16x16x32_bf16 v[110:113], v[206:209], v[182:185], v[110:113]
	v_mfma_f32_16x16x32_bf16 v[102:105], v[214:217], v[182:185], v[102:105]
	v_mfma_f32_16x16x32_bf16 v[94:97], v[206:209], v[190:193], v[94:97]
	v_mfma_f32_16x16x32_bf16 v[86:89], v[214:217], v[190:193], v[86:89]
	v_mfma_f32_16x16x32_bf16 v[78:81], v[206:209], v[198:201], v[78:81]
	v_mfma_f32_16x16x32_bf16 v[70:73], v[214:217], v[198:201], v[70:73]
	s_mov_b32 m0, s72
	v_lshl_add_u64 v[226:227], s[30:31], 0, v[134:135]
	s_barrier
; #define PG8_STAGE(bufoff, gbase, voff) do { _Pragma("unroll") for (int _i = 0; _i < 2; ++_i) \
;     __builtin_amdgcn_global_load_lds((const unsigned*)((const char*)(gbase) + (voff)[_i]), (PG8_LAS unsigned*)(lds + (bufoff) + ldsw + _i * 8192), 16, 0, 0); } while (0)
; #define PG8_LDA(dst, b, h) do { _Pragma("unroll") for (int m = 0; m < 4; ++m) _Pragma("unroll") for (int k = 0; k < 2; ++k) dst[m][k] = *(const PG8_LAS bf16x8*)(lds + PG8_SA(b, h) + aoff + m * 2048 + k * 1024); } while (0)
; #define PG8_LDB(dst, b, h) do { _Pragma("unroll") for (int n = 0; n < 2; ++n) _Pragma("unroll") for (int k = 0; k < 2; ++k) dst[n][k] = *(const PG8_LAS bf16x8*)(lds + PG8_SB(b, h) + boff + n * 2048 + k * 1024); } while (0)
; #define PG8_MMA(ai, bj, At, Bt) do { __builtin_amdgcn_s_setprio(1); _Pragma("unroll") for (int m = 0; m < 4; ++m) _Pragma("unroll") for (int n = 0; n < 2; ++n) _Pragma("unroll") for (int k = 0; k < 2; ++k) \
;     acc[ai][bj][m][n] = __builtin_amdgcn_mfma_f32_16x16x32_bf16(Bt[n][k], At[m][k], acc[ai][bj][m][n], 0, 0, 0); __builtin_amdgcn_s_setprio(0); } while (0)
; #define PG8_WAIT_V(n) asm volatile("s_waitcnt vmcnt(" #n ")" ::: "memory")
; #define PG8_WAIT_L(n) asm volatile("s_waitcnt lgkmcnt(" #n ")" ::: "memory")
; #define PG8_BAR __builtin_amdgcn_s_barrier()
; #define PG8_SCHED __builtin_amdgcn_sched_barrier(0)
; template <class Epi>
; DI void gemm_phase(const bf16_t* __restrict__ gA, const bf16_t* __restrict__ gBt, int M, int N, int K, const Epi& E, char* lds_generic) {
;     ...
;       PG8_LDA(At, 0, 1); PG8_STAGE(PG8_SA(0, 0), a2, voffA);
;       PG8_BAR; PG8_WAIT_L(0); PG8_MMA(1, 0, At, B0); PG8_BAR; PG8_SCHED;
;       PG8_STAGE(PG8_SB(0, 1), b2 + hstep, voffB);
;       PG8_WAIT_V(6); PG8_BAR; PG8_MMA(1, 1, At, B1); PG8_BAR;
;       PG8_LDB(B0, 1, 0); PG8_SCHED; PG8_LDA(At, 1, 0); PG8_STAGE(PG8_SA(0, 1), a2 + hstep, voffA);
;       PG8_WAIT_L(8); PG8_BAR; PG8_WAIT_L(0); PG8_MMA(0, 0, At, B0); PG8_BAR; PG8_SCHED;
	ds_read_b128 v[170:173], v154 offset:16384
	ds_read_b128 v[174:177], v154 offset:17408
	ds_read_b128 v[178:181], v154 offset:18432
	ds_read_b128 v[182:185], v154 offset:19456
	ds_read_b128 v[186:189], v154 offset:20480
	ds_read_b128 v[190:193], v154 offset:21504
	ds_read_b128 v[194:197], v154 offset:22528
	ds_read_b128 v[198:201], v154 offset:23552
	global_load_lds_dwordx4 v[226:227], off
	v_lshl_add_u64 v[228:229], s[30:31], 0, v[136:137]
	s_mov_b32 m0, s58
	s_nop 0
	global_load_lds_dwordx4 v[228:229], off
	s_barrier
	s_waitcnt lgkmcnt(0)
	s_waitcnt lgkmcnt(0)
	v_mfma_f32_16x16x32_bf16 v[66:69], v[50:53], v[170:173], v[66:69]
	v_mfma_f32_16x16x32_bf16 v[58:61], v[158:161], v[170:173], v[58:61]
	v_mfma_f32_16x16x32_bf16 v[46:49], v[50:53], v[178:181], v[46:49]
	v_mfma_f32_16x16x32_bf16 v[38:41], v[158:161], v[178:181], v[38:41]
	v_mfma_f32_16x16x32_bf16 v[30:33], v[50:53], v[186:189], v[30:33]
	v_mfma_f32_16x16x32_bf16 v[22:25], v[158:161], v[186:189], v[22:25]
	v_mfma_f32_16x16x32_bf16 v[14:17], v[50:53], v[194:197], v[14:17]
	v_mfma_f32_16x16x32_bf16 v[6:9], v[158:161], v[194:197], v[6:9]
	v_mfma_f32_16x16x32_bf16 v[66:69], v[146:149], v[174:177], v[66:69]
	v_mfma_f32_16x16x32_bf16 v[58:61], v[166:169], v[174:177], v[58:61]
	v_mfma_f32_16x16x32_bf16 v[46:49], v[146:149], v[182:185], v[46:49]
	v_mfma_f32_16x16x32_bf16 v[38:41], v[166:169], v[182:185], v[38:41]
	v_mfma_f32_16x16x32_bf16 v[30:33], v[146:149], v[190:193], v[30:33]
	v_mfma_f32_16x16x32_bf16 v[22:25], v[166:169], v[190:193], v[22:25]
	v_mfma_f32_16x16x32_bf16 v[14:17], v[146:149], v[198:201], v[14:17]
	v_mfma_f32_16x16x32_bf16 v[6:9], v[166:169], v[198:201], v[6:9]
	s_barrier
	s_add_u32 s24, s28, 0x40000
	s_addc_u32 s25, s29, 0
	s_mov_b32 m0, s59
	v_lshl_add_u64 v[50:51], s[24:25], 0, v[0:1]
	global_load_lds_dwordx4 v[50:51], off
	v_lshl_add_u64 v[50:51], s[24:25], 0, v[138:139]
	s_mov_b32 m0, s62
	s_nop 0
	global_load_lds_dwordx4 v[50:51], off
	s_waitcnt vmcnt(6)
	s_barrier
	v_mfma_f32_16x16x32_bf16 v[54:57], v[210:213], v[170:173], v[54:57]
	v_mfma_f32_16x16x32_bf16 v[42:45], v[202:205], v[178:181], v[42:45]
	v_mfma_f32_16x16x32_bf16 v[34:37], v[210:213], v[178:181], v[34:37]
	v_mfma_f32_16x16x32_bf16 v[26:29], v[202:205], v[186:189], v[26:29]
	v_mfma_f32_16x16x32_bf16 v[18:21], v[210:213], v[186:189], v[18:21]
	v_mfma_f32_16x16x32_bf16 v[10:13], v[202:205], v[194:197], v[10:13]
	v_mfma_f32_16x16x32_bf16 v[2:5], v[210:213], v[194:197], v[2:5]
	v_mfma_f32_16x16x32_bf16 v[50:53], v[202:205], v[170:173], v[62:65]
	v_mfma_f32_16x16x32_bf16 v[54:57], v[214:217], v[174:177], v[54:57]
	v_mfma_f32_16x16x32_bf16 v[42:45], v[206:209], v[182:185], v[42:45]
	v_mfma_f32_16x16x32_bf16 v[34:37], v[214:217], v[182:185], v[34:37]
	v_mfma_f32_16x16x32_bf16 v[26:29], v[206:209], v[190:193], v[26:29]
	v_mfma_f32_16x16x32_bf16 v[18:21], v[214:217], v[190:193], v[18:21]
	v_mfma_f32_16x16x32_bf16 v[10:13], v[206:209], v[198:201], v[10:13]
	v_mfma_f32_16x16x32_bf16 v[2:5], v[214:217], v[198:201], v[2:5]
	v_mfma_f32_16x16x32_bf16 v[50:53], v[206:209], v[174:177], v[50:53]
	v_or_b32_e32 v62, 0x18000, v155
	v_add_u32_e32 v146, 0x18400, v155
	v_add_u32_e32 v158, 0x18800, v155
	s_barrier
.Lup605_p5:
	ds_read_b128 v[62:65], v62
	ds_read_b128 v[146:149], v146
	v_add_u32_e32 v163, 0x18c00, v155
	ds_read_b128 v[158:161], v158
	ds_read_b128 v[166:169], v163
	s_add_u32 s24, s30, 0x40000
	s_addc_u32 s25, s31, 0
	s_mov_b32 m0, s7
	v_lshl_add_u64 v[202:203], s[24:25], 0, v[134:135]
	ds_read_b128 v[170:173], v154 offset:32768
	ds_read_b128 v[174:177], v154 offset:33792
	ds_read_b128 v[178:181], v154 offset:34816
	ds_read_b128 v[182:185], v154 offset:35840
	ds_read_b128 v[186:189], v154 offset:36864
	ds_read_b128 v[190:193], v154 offset:37888
	ds_read_b128 v[194:197], v154 offset:38912
	ds_read_b128 v[198:201], v154 offset:39936
	global_load_lds_dwordx4 v[202:203], off
	v_lshl_add_u64 v[202:203], s[24:25], 0, v[136:137]
	s_mov_b32 m0, s12
	s_nop 0
	global_load_lds_dwordx4 v[202:203], off
	s_waitcnt lgkmcnt(8)
	s_barrier
	s_waitcnt lgkmcnt(0)
	s_waitcnt lgkmcnt(0)
	v_mfma_f32_16x16x32_bf16 v[130:133], v[62:65], v[170:173], v[130:133]
	v_mfma_f32_16x16x32_bf16 v[122:125], v[158:161], v[170:173], v[122:125]
	v_mfma_f32_16x16x32_bf16 v[114:117], v[62:65], v[178:181], v[114:117]
	v_mfma_f32_16x16x32_bf16 v[106:109], v[158:161], v[178:181], v[106:109]
	v_mfma_f32_16x16x32_bf16 v[98:101], v[62:65], v[186:189], v[98:101]
	v_mfma_f32_16x16x32_bf16 v[90:93], v[158:161], v[186:189], v[90:93]
	v_mfma_f32_16x16x32_bf16 v[82:85], v[62:65], v[194:197], v[82:85]
	v_mfma_f32_16x16x32_bf16 v[74:77], v[158:161], v[194:197], v[74:77]
	v_mfma_f32_16x16x32_bf16 v[130:133], v[146:149], v[174:177], v[130:133]
	v_mfma_f32_16x16x32_bf16 v[122:125], v[166:169], v[174:177], v[122:125]
	v_mfma_f32_16x16x32_bf16 v[114:117], v[146:149], v[182:185], v[114:117]
	v_mfma_f32_16x16x32_bf16 v[106:109], v[166:169], v[182:185], v[106:109]
	v_mfma_f32_16x16x32_bf16 v[98:101], v[146:149], v[190:193], v[98:101]
	v_mfma_f32_16x16x32_bf16 v[90:93], v[166:169], v[190:193], v[90:93]
	v_mfma_f32_16x16x32_bf16 v[82:85], v[146:149], v[198:201], v[82:85]
	v_mfma_f32_16x16x32_bf16 v[74:77], v[166:169], v[198:201], v[74:77]
	s_barrier
; #define PG8_STAGE(bufoff, gbase, voff) do { _Pragma("unroll") for (int _i = 0; _i < 2; ++_i) \
;     __builtin_amdgcn_global_load_lds((const unsigned*)((const char*)(gbase) + (voff)[_i]), (PG8_LAS unsigned*)(lds + (bufoff) + ldsw + _i * 8192), 16, 0, 0); } while (0)
; #define PG8_LDA(dst, b, h) do { _Pragma("unroll") for (int m = 0; m < 4; ++m) _Pragma("unroll") for (int k = 0; k < 2; ++k) dst[m][k] = *(const PG8_LAS bf16x8*)(lds + PG8_SA(b, h) + aoff + m * 2048 + k * 1024); } while (0)
; #define PG8_LDB(dst, b, h) do { _Pragma("unroll") for (int n = 0; n < 2; ++n) _Pragma("unroll") for (int k = 0; k < 2; ++k) dst[n][k] = *(const PG8_LAS bf16x8*)(lds + PG8_SB(b, h) + boff + n * 2048 + k * 1024); } while (0)
; #define PG8_MMA(ai, bj, At, Bt) do { __builtin_amdgcn_s_setprio(1); _Pragma("unroll") for (int m = 0; m < 4; ++m) _Pragma("unroll") for (int n = 0; n < 2; ++n) _Pragma("unroll") for (int k = 0; k < 2; ++k) \
;     acc[ai][bj][m][n] = __builtin_amdgcn_mfma_f32_16x16x32_bf16(Bt[n][k], At[m][k], acc[ai][bj][m][n], 0, 0, 0); __builtin_amdgcn_s_setprio(0); } while (0)
; #define PG8_WAIT_V(n) asm volatile("s_waitcnt vmcnt(" #n ")" ::: "memory")
; #define PG8_WAIT_L(n) asm volatile("s_waitcnt lgkmcnt(" #n ")" ::: "memory")
; #define PG8_BAR __builtin_amdgcn_s_barrier()
; #define PG8_SCHED __builtin_amdgcn_sched_barrier(0)
; template <class Epi>
; DI void gemm_phase(const bf16_t* __restrict__ gA, const bf16_t* __restrict__ gBt, int M, int N, int K, const Epi& E, char* lds_generic) {
;     ...
;       PG8_LDB(B1, 1, 1); PG8_STAGE(PG8_SB(1, 0), b3, voffB);
;       PG8_BAR; PG8_WAIT_L(0); PG8_MMA(0, 1, At, B1); PG8_BAR;
;       PG8_LDA(At, 1, 1); PG8_STAGE(PG8_SA(1, 0), a3, voffA);
;       PG8_BAR; PG8_WAIT_L(0); PG8_MMA(1, 0, At, B0); PG8_BAR; PG8_SCHED;
;       PG8_STAGE(PG8_SB(1, 1), b3 + hstep, voffB);
;       PG8_WAIT_V(6); PG8_BAR; PG8_MMA(1, 1, At, B1); PG8_BAR;
	v_or_b32_e32 v163, 0x1c000, v155
	s_mov_b32 m0, s13
	v_add_u32_e32 v165, 0x1c400, v155
	ds_read_b128 v[202:205], v163
	ds_read_b128 v[206:209], v165
	v_add_u32_e32 v163, 0x1c800, v155
	v_lshl_add_u64 v[218:219], v[218:219], 0, s[10:11]
	v_add_u32_e32 v165, 0x1cc00, v155
	ds_read_b128 v[210:213], v163
	ds_read_b128 v[214:217], v165
	global_load_lds_dwordx4 v[218:219], off
	v_lshl_add_u64 v[218:219], v[220:221], 0, s[10:11]
	s_mov_b32 m0, s35
	s_nop 0
	global_load_lds_dwordx4 v[218:219], off
	s_barrier
	s_waitcnt lgkmcnt(0)
	s_waitcnt lgkmcnt(0)
	v_mfma_f32_16x16x32_bf16 v[126:129], v[202:205], v[170:173], v[126:129]
	v_mfma_f32_16x16x32_bf16 v[118:121], v[210:213], v[170:173], v[118:121]
	v_mfma_f32_16x16x32_bf16 v[110:113], v[202:205], v[178:181], v[110:113]
	v_mfma_f32_16x16x32_bf16 v[102:105], v[210:213], v[178:181], v[102:105]
	v_mfma_f32_16x16x32_bf16 v[94:97], v[202:205], v[186:189], v[94:97]
	v_mfma_f32_16x16x32_bf16 v[86:89], v[210:213], v[186:189], v[86:89]
	v_mfma_f32_16x16x32_bf16 v[78:81], v[202:205], v[194:197], v[78:81]
	v_mfma_f32_16x16x32_bf16 v[70:73], v[210:213], v[194:197], v[70:73]
	v_mfma_f32_16x16x32_bf16 v[126:129], v[206:209], v[174:177], v[126:129]
	v_mfma_f32_16x16x32_bf16 v[118:121], v[214:217], v[174:177], v[118:121]
	v_mfma_f32_16x16x32_bf16 v[110:113], v[206:209], v[182:185], v[110:113]
	v_mfma_f32_16x16x32_bf16 v[102:105], v[214:217], v[182:185], v[102:105]
	v_mfma_f32_16x16x32_bf16 v[94:97], v[206:209], v[190:193], v[94:97]
	v_mfma_f32_16x16x32_bf16 v[86:89], v[214:217], v[190:193], v[86:89]
	v_mfma_f32_16x16x32_bf16 v[78:81], v[206:209], v[198:201], v[78:81]
	v_mfma_f32_16x16x32_bf16 v[70:73], v[214:217], v[198:201], v[70:73]
	s_mov_b32 m0, s53
	v_lshl_add_u64 v[218:219], v[226:227], 0, s[10:11]
	s_barrier
	ds_read_b128 v[170:173], v154 offset:49152
	ds_read_b128 v[174:177], v154 offset:50176
	ds_read_b128 v[178:181], v154 offset:51200
	ds_read_b128 v[182:185], v154 offset:52224
	ds_read_b128 v[186:189], v154 offset:53248
	ds_read_b128 v[190:193], v154 offset:54272
	ds_read_b128 v[194:197], v154 offset:55296
	ds_read_b128 v[198:201], v154 offset:56320
	global_load_lds_dwordx4 v[218:219], off
	v_lshl_add_u64 v[218:219], v[228:229], 0, s[10:11]
	s_mov_b32 m0, s74
	s_nop 0
	global_load_lds_dwordx4 v[218:219], off
	s_barrier
	s_waitcnt lgkmcnt(0)
	s_waitcnt lgkmcnt(0)
	v_mfma_f32_16x16x32_bf16 v[66:69], v[62:65], v[170:173], v[66:69]
	v_mfma_f32_16x16x32_bf16 v[58:61], v[158:161], v[170:173], v[58:61]
	v_mfma_f32_16x16x32_bf16 v[46:49], v[62:65], v[178:181], v[46:49]
	v_mfma_f32_16x16x32_bf16 v[38:41], v[158:161], v[178:181], v[38:41]
	v_mfma_f32_16x16x32_bf16 v[30:33], v[62:65], v[186:189], v[30:33]
	v_mfma_f32_16x16x32_bf16 v[22:25], v[158:161], v[186:189], v[22:25]
	v_mfma_f32_16x16x32_bf16 v[14:17], v[62:65], v[194:197], v[14:17]
	v_mfma_f32_16x16x32_bf16 v[6:9], v[158:161], v[194:197], v[6:9]
	v_mfma_f32_16x16x32_bf16 v[66:69], v[146:149], v[174:177], v[66:69]
	v_mfma_f32_16x16x32_bf16 v[58:61], v[166:169], v[174:177], v[58:61]
	v_mfma_f32_16x16x32_bf16 v[46:49], v[146:149], v[182:185], v[46:49]
	v_mfma_f32_16x16x32_bf16 v[38:41], v[166:169], v[182:185], v[38:41]
	v_mfma_f32_16x16x32_bf16 v[30:33], v[146:149], v[190:193], v[30:33]
	v_mfma_f32_16x16x32_bf16 v[22:25], v[166:169], v[190:193], v[22:25]
	v_mfma_f32_16x16x32_bf16 v[14:17], v[146:149], v[198:201], v[14:17]
	v_mfma_f32_16x16x32_bf16 v[6:9], v[166:169], v[198:201], v[6:9]
	s_barrier
	s_add_u32 s24, s28, 0x40080
	s_addc_u32 s25, s29, 0
	s_mov_b32 m0, s60
	v_lshl_add_u64 v[62:63], s[24:25], 0, v[0:1]
	global_load_lds_dwordx4 v[62:63], off
	v_lshl_add_u64 v[62:63], s[24:25], 0, v[138:139]
	s_mov_b32 m0, s6
	s_nop 0
	global_load_lds_dwordx4 v[62:63], off
	s_waitcnt vmcnt(6)
	s_barrier
	v_mfma_f32_16x16x32_bf16 v[50:53], v[202:205], v[170:173], v[50:53]
	v_mfma_f32_16x16x32_bf16 v[62:65], v[206:209], v[174:177], v[50:53]
	v_mfma_f32_16x16x32_bf16 v[50:53], v[210:213], v[170:173], v[54:57]
	v_mfma_f32_16x16x32_bf16 v[42:45], v[202:205], v[178:181], v[42:45]
	v_mfma_f32_16x16x32_bf16 v[34:37], v[210:213], v[178:181], v[34:37]
	v_mfma_f32_16x16x32_bf16 v[26:29], v[202:205], v[186:189], v[26:29]
	v_mfma_f32_16x16x32_bf16 v[18:21], v[210:213], v[186:189], v[18:21]
	v_mfma_f32_16x16x32_bf16 v[10:13], v[202:205], v[194:197], v[10:13]
	v_mfma_f32_16x16x32_bf16 v[2:5], v[210:213], v[194:197], v[2:5]
	v_mfma_f32_16x16x32_bf16 v[54:57], v[214:217], v[174:177], v[50:53]
	v_mfma_f32_16x16x32_bf16 v[42:45], v[206:209], v[182:185], v[42:45]
	v_mfma_f32_16x16x32_bf16 v[34:37], v[214:217], v[182:185], v[34:37]
	v_mfma_f32_16x16x32_bf16 v[26:29], v[206:209], v[190:193], v[26:29]
	v_mfma_f32_16x16x32_bf16 v[18:21], v[214:217], v[190:193], v[18:21]
	v_mfma_f32_16x16x32_bf16 v[10:13], v[206:209], v[198:201], v[10:13]
	v_mfma_f32_16x16x32_bf16 v[2:5], v[214:217], v[198:201], v[2:5]
	s_add_i32 s23, s23, 2
	s_add_u32 vcc_lo, vcc_lo, 0x100
	s_addc_u32 vcc_hi, vcc_hi, 0
	s_add_u32 s87, s87, 0x100
	s_addc_u32 s22, s22, 0
	s_cmp_gt_u32 s23, 13
	s_barrier
	s_cbranch_scc0 .LBB0_605
	v_mov_b32_e32 v50, 0
	s_and_b64 vcc, exec, s[38:39]
	v_mov_b32_e32 v51, 0
	v_mov_b32_e32 v52, 0
	v_mov_b32_e32 v53, 0
	s_cbranch_vccz .LBB0_608
	v_lshl_add_u32 v50, s86, 8, v150
	v_ashrrev_i32_e32 v51, 31, v50
	v_lshlrev_b64 v[50:51], 5, v[50:51]
	v_lshl_add_u64 v[50:51], v[140:141], 0, v[50:51]
	global_load_dwordx4 v[50:53], v[50:51], off

; #define PG8_STAGE(bufoff, gbase, voff) do { _Pragma("unroll") for (int _i = 0; _i < 2; ++_i) \
;     __builtin_amdgcn_global_load_lds((const unsigned*)((const char*)(gbase) + (voff)[_i]), (PG8_LAS unsigned*)(lds + (bufoff) + ldsw + _i * 8192), 16, 0, 0); } while (0)
; #define PG8_LDA(dst, b, h) do { _Pragma("unroll") for (int m = 0; m < 4; ++m) _Pragma("unroll") for (int k = 0; k < 2; ++k) dst[m][k] = *(const PG8_LAS bf16x8*)(lds + PG8_SA(b, h) + aoff + m * 2048 + k * 1024); } while (0)
; #define PG8_LDB(dst, b, h) do { _Pragma("unroll") for (int n = 0; n < 2; ++n) _Pragma("unroll") for (int k = 0; k < 2; ++k) dst[n][k] = *(const PG8_LAS bf16x8*)(lds + PG8_SB(b, h) + boff + n * 2048 + k * 1024); } while (0)
; #define PG8_MMA(ai, bj, At, Bt) do { __builtin_amdgcn_s_setprio(1); _Pragma("unroll") for (int m = 0; m < 4; ++m) _Pragma("unroll") for (int n = 0; n < 2; ++n) _Pragma("unroll") for (int k = 0; k < 2; ++k) \
;     acc[ai][bj][m][n] = __builtin_amdgcn_mfma_f32_16x16x32_bf16(Bt[n][k], At[m][k], acc[ai][bj][m][n], 0, 0, 0); __builtin_amdgcn_s_setprio(0); } while (0)
; #define PG8_WAIT_L(n) asm volatile("s_waitcnt lgkmcnt(" #n ")" ::: "memory")
; #define PG8_BAR __builtin_amdgcn_s_barrier()
; #define PG8_SCHED __builtin_amdgcn_sched_barrier(0)
; template <class Epi>
; DI void gemm_phase(const bf16_t* __restrict__ gA, const bf16_t* __restrict__ gBt, int M, int N, int K, const Epi& E, char* lds_generic) {
;     ...
;     for (int t = 0; t < nt; t += 2) {
;       const bool last = (t == nt - 2);
;       const char* a1 = cA + (size_t)(t + 1) * kstep;
;       const char* a2 = last ? nA : cA + (size_t)(t + 2) * kstep; const char* b2 = last ? nB : cB + (size_t)(t + 2) * kstep;
;       const char* a3 = a2 + kstep; const char* b3 = b2 + kstep;
;       PG8_LDB(B0, 0, 0); PG8_SCHED; PG8_LDA(At, 0, 0); PG8_STAGE(PG8_SA(1, 1), a1 + hstep, voffA);
;       PG8_WAIT_L(8); PG8_BAR; PG8_WAIT_L(0); PG8_MMA(0, 0, At, B0); PG8_BAR; PG8_SCHED;
;       PG8_LDB(B1, 0, 1); PG8_STAGE(PG8_SB(0, 0), b2, voffB);
;       PG8_BAR; PG8_WAIT_L(0); PG8_MMA(0, 1, At, B1); PG8_BAR;
;       PG8_LDA(At, 0, 1); PG8_STAGE(PG8_SA(0, 0), a2, voffA);
;       PG8_BAR; PG8_WAIT_L(0); PG8_MMA(1, 0, At, B0); PG8_BAR; PG8_SCHED;
.LBB0_684:
	v_or_b32_e32 v140, 0x10000, v146
	v_add_u32_e32 v148, 0x10400, v146
	v_add_u32_e32 v152, 0x10800, v146
	v_add_u32_e32 v156, 0x10c00, v146
	ds_read_b128 v[140:143], v140
	ds_read_b128 v[148:151], v148
	ds_read_b128 v[152:155], v152
	ds_read_b128 v[156:159], v156
	s_add_u32 s28, s88, 0x100
	s_addc_u32 s29, s89, 0
	s_cmp_eq_u32 s23, 40
	s_cselect_b32 s91, s87, s29
	s_cselect_b32 s90, s86, s28
	s_cselect_b32 s31, s1, s22
	s_cselect_b32 s30, s0, s21
	v_lshl_add_u64 v[160:161], s[88:89], 0, v[136:137]
	s_add_i32 m0, s12, 0xc000
	ds_read_b128 v[166:169], v145
	ds_read_b128 v[170:173], v145 offset:1024
	ds_read_b128 v[174:177], v145 offset:2048
	ds_read_b128 v[178:181], v145 offset:3072
	ds_read_b128 v[182:185], v145 offset:4096
	ds_read_b128 v[186:189], v145 offset:5120
	ds_read_b128 v[190:193], v145 offset:6144
	ds_read_b128 v[194:197], v145 offset:7168
	global_load_lds_dwordx4 v[160:161], off
	v_lshl_add_u64 v[160:161], s[88:89], 0, v[138:139]
	s_add_i32 m0, s12, 0xe000
	s_nop 0
	global_load_lds_dwordx4 v[160:161], off
	s_waitcnt lgkmcnt(8)
	s_barrier
	s_waitcnt lgkmcnt(0)
	s_waitcnt lgkmcnt(0)
	v_mfma_f32_16x16x32_bf16 v[126:129], v[140:143], v[166:169], v[126:129]
	v_mfma_f32_16x16x32_bf16 v[122:125], v[152:155], v[166:169], v[122:125]
	v_mfma_f32_16x16x32_bf16 v[110:113], v[140:143], v[174:177], v[110:113]
	v_mfma_f32_16x16x32_bf16 v[106:109], v[152:155], v[174:177], v[106:109]
	v_mfma_f32_16x16x32_bf16 v[94:97], v[140:143], v[182:185], v[94:97]
	v_mfma_f32_16x16x32_bf16 v[90:93], v[152:155], v[182:185], v[90:93]
	v_mfma_f32_16x16x32_bf16 v[78:81], v[140:143], v[190:193], v[78:81]
	v_mfma_f32_16x16x32_bf16 v[74:77], v[152:155], v[190:193], v[74:77]
	v_mfma_f32_16x16x32_bf16 v[126:129], v[148:151], v[170:173], v[126:129]
	v_mfma_f32_16x16x32_bf16 v[122:125], v[156:159], v[170:173], v[122:125]
	v_mfma_f32_16x16x32_bf16 v[110:113], v[148:151], v[178:181], v[110:113]
	v_mfma_f32_16x16x32_bf16 v[106:109], v[156:159], v[178:181], v[106:109]
	v_mfma_f32_16x16x32_bf16 v[94:97], v[148:151], v[186:189], v[94:97]
	v_mfma_f32_16x16x32_bf16 v[90:93], v[156:159], v[186:189], v[90:93]
	v_mfma_f32_16x16x32_bf16 v[78:81], v[148:151], v[194:197], v[78:81]
	v_mfma_f32_16x16x32_bf16 v[74:77], v[156:159], v[194:197], v[74:77]
	s_barrier
	v_or_b32_e32 v160, 0x14000, v146
	v_add_u32_e32 v161, 0x14400, v146
	ds_read_b128 v[198:201], v160
	ds_read_b128 v[202:205], v161
	v_add_u32_e32 v160, 0x14800, v146
	v_add_u32_e32 v161, 0x14c00, v146
	s_mov_b32 m0, s13
	ds_read_b128 v[206:209], v160
	ds_read_b128 v[210:213], v161
	v_lshl_add_u64 v[160:161], s[30:31], 0, v[0:1]
	global_load_lds_dwordx4 v[160:161], off
	v_lshl_add_u64 v[214:215], s[30:31], 0, v[134:135]
	s_mov_b32 m0, s14
	s_nop 0
	global_load_lds_dwordx4 v[214:215], off
	s_barrier
	s_waitcnt lgkmcnt(0)
	s_waitcnt lgkmcnt(0)
	v_mfma_f32_16x16x32_bf16 v[118:121], v[198:201], v[166:169], v[118:121]
	v_mfma_f32_16x16x32_bf16 v[114:117], v[206:209], v[166:169], v[114:117]
	v_mfma_f32_16x16x32_bf16 v[102:105], v[198:201], v[174:177], v[102:105]
	v_mfma_f32_16x16x32_bf16 v[98:101], v[206:209], v[174:177], v[98:101]
	v_mfma_f32_16x16x32_bf16 v[86:89], v[198:201], v[182:185], v[86:89]
	v_mfma_f32_16x16x32_bf16 v[82:85], v[206:209], v[182:185], v[82:85]
	v_mfma_f32_16x16x32_bf16 v[70:73], v[198:201], v[190:193], v[70:73]
	v_mfma_f32_16x16x32_bf16 v[66:69], v[206:209], v[190:193], v[66:69]
	v_mfma_f32_16x16x32_bf16 v[118:121], v[202:205], v[170:173], v[118:121]
	v_mfma_f32_16x16x32_bf16 v[114:117], v[210:213], v[170:173], v[114:117]
	v_mfma_f32_16x16x32_bf16 v[102:105], v[202:205], v[178:181], v[102:105]
	v_mfma_f32_16x16x32_bf16 v[98:101], v[210:213], v[178:181], v[98:101]
	v_mfma_f32_16x16x32_bf16 v[86:89], v[202:205], v[186:189], v[86:89]
	v_mfma_f32_16x16x32_bf16 v[82:85], v[210:213], v[186:189], v[82:85]
	v_mfma_f32_16x16x32_bf16 v[70:73], v[202:205], v[194:197], v[70:73]
	v_mfma_f32_16x16x32_bf16 v[66:69], v[210:213], v[194:197], v[66:69]
	s_mov_b32 m0, s12
	v_lshl_add_u64 v[216:217], s[90:91], 0, v[130:131]
	s_barrier
	ds_read_b128 v[166:169], v145 offset:16384
	ds_read_b128 v[170:173], v145 offset:17408
	ds_read_b128 v[174:177], v145 offset:18432
	ds_read_b128 v[178:181], v145 offset:19456
	ds_read_b128 v[182:185], v145 offset:20480
	ds_read_b128 v[186:189], v145 offset:21504
	ds_read_b128 v[190:193], v145 offset:22528
	ds_read_b128 v[194:197], v145 offset:23552
	global_load_lds_dwordx4 v[216:217], off
	v_lshl_add_u64 v[218:219], s[90:91], 0, v[132:133]
	s_mov_b32 m0, s15
	s_nop 0
	global_load_lds_dwordx4 v[218:219], off
	s_barrier
	s_waitcnt lgkmcnt(0)
	s_waitcnt lgkmcnt(0)
	v_mfma_f32_16x16x32_bf16 v[62:65], v[140:143], v[166:169], v[62:65]
	v_mfma_f32_16x16x32_bf16 v[58:61], v[152:155], v[166:169], v[58:61]
	v_mfma_f32_16x16x32_bf16 v[46:49], v[140:143], v[174:177], v[46:49]
	v_mfma_f32_16x16x32_bf16 v[42:45], v[152:155], v[174:177], v[42:45]
	v_mfma_f32_16x16x32_bf16 v[30:33], v[140:143], v[182:185], v[30:33]
	v_mfma_f32_16x16x32_bf16 v[26:29], v[152:155], v[182:185], v[26:29]
	v_mfma_f32_16x16x32_bf16 v[14:17], v[140:143], v[190:193], v[14:17]
	v_mfma_f32_16x16x32_bf16 v[10:13], v[152:155], v[190:193], v[10:13]
	v_mfma_f32_16x16x32_bf16 v[62:65], v[148:151], v[170:173], v[62:65]
	v_mfma_f32_16x16x32_bf16 v[58:61], v[156:159], v[170:173], v[58:61]
	v_mfma_f32_16x16x32_bf16 v[46:49], v[148:151], v[178:181], v[46:49]
	v_mfma_f32_16x16x32_bf16 v[42:45], v[156:159], v[178:181], v[42:45]
	v_mfma_f32_16x16x32_bf16 v[30:33], v[148:151], v[186:189], v[30:33]
	v_mfma_f32_16x16x32_bf16 v[26:29], v[156:159], v[186:189], v[26:29]
	v_mfma_f32_16x16x32_bf16 v[14:17], v[148:151], v[194:197], v[14:17]
	v_mfma_f32_16x16x32_bf16 v[10:13], v[156:159], v[194:197], v[10:13]
	s_barrier
; #define PG8_STAGE(bufoff, gbase, voff) do { _Pragma("unroll") for (int _i = 0; _i < 2; ++_i) \
;     __builtin_amdgcn_global_load_lds((const unsigned*)((const char*)(gbase) + (voff)[_i]), (PG8_LAS unsigned*)(lds + (bufoff) + ldsw + _i * 8192), 16, 0, 0); } while (0)
; #define PG8_LDA(dst, b, h) do { _Pragma("unroll") for (int m = 0; m < 4; ++m) _Pragma("unroll") for (int k = 0; k < 2; ++k) dst[m][k] = *(const PG8_LAS bf16x8*)(lds + PG8_SA(b, h) + aoff + m * 2048 + k * 1024); } while (0)
; #define PG8_LDB(dst, b, h) do { _Pragma("unroll") for (int n = 0; n < 2; ++n) _Pragma("unroll") for (int k = 0; k < 2; ++k) dst[n][k] = *(const PG8_LAS bf16x8*)(lds + PG8_SB(b, h) + boff + n * 2048 + k * 1024); } while (0)
; #define PG8_MMA(ai, bj, At, Bt) do { __builtin_amdgcn_s_setprio(1); _Pragma("unroll") for (int m = 0; m < 4; ++m) _Pragma("unroll") for (int n = 0; n < 2; ++n) _Pragma("unroll") for (int k = 0; k < 2; ++k) \
;     acc[ai][bj][m][n] = __builtin_amdgcn_mfma_f32_16x16x32_bf16(Bt[n][k], At[m][k], acc[ai][bj][m][n], 0, 0, 0); __builtin_amdgcn_s_setprio(0); } while (0)
; #define PG8_WAIT_V(n) asm volatile("s_waitcnt vmcnt(" #n ")" ::: "memory")
; #define PG8_WAIT_L(n) asm volatile("s_waitcnt lgkmcnt(" #n ")" ::: "memory")
; #define PG8_BAR __builtin_amdgcn_s_barrier()
; #define PG8_SCHED __builtin_amdgcn_sched_barrier(0)
; template <class Epi>
; DI void gemm_phase(const bf16_t* __restrict__ gA, const bf16_t* __restrict__ gBt, int M, int N, int K, const Epi& E, char* lds_generic) {
;     ...
;       PG8_STAGE(PG8_SB(0, 1), b2 + hstep, voffB);
;       PG8_WAIT_V(6); PG8_BAR; PG8_MMA(1, 1, At, B1); PG8_BAR;
;       PG8_LDB(B0, 1, 0); PG8_SCHED; PG8_LDA(At, 1, 0); PG8_STAGE(PG8_SA(0, 1), a2 + hstep, voffA);
;       PG8_WAIT_L(8); PG8_BAR; PG8_WAIT_L(0); PG8_MMA(0, 0, At, B0); PG8_BAR; PG8_SCHED;
;       PG8_LDB(B1, 1, 1); PG8_STAGE(PG8_SB(1, 0), b3, voffB);
;       PG8_BAR; PG8_WAIT_L(0); PG8_MMA(0, 1, At, B1); PG8_BAR;
;       PG8_LDA(At, 1, 1); PG8_STAGE(PG8_SA(1, 0), a3, voffA);
	s_add_u32 s24, s30, 0xb0000
	s_addc_u32 s25, s31, 0
	s_mov_b32 m0, s18
	v_lshl_add_u64 v[140:141], s[24:25], 0, v[0:1]
	global_load_lds_dwordx4 v[140:141], off
	v_lshl_add_u64 v[140:141], s[24:25], 0, v[134:135]
	s_mov_b32 m0, s35
	s_nop 0
	global_load_lds_dwordx4 v[140:141], off
	s_waitcnt vmcnt(6)
	s_barrier
	v_mfma_f32_16x16x32_bf16 v[54:57], v[198:201], v[166:169], v[54:57]
	v_mfma_f32_16x16x32_bf16 v[50:53], v[206:209], v[166:169], v[50:53]
	v_mfma_f32_16x16x32_bf16 v[38:41], v[198:201], v[174:177], v[38:41]
	v_mfma_f32_16x16x32_bf16 v[34:37], v[206:209], v[174:177], v[34:37]
	v_mfma_f32_16x16x32_bf16 v[22:25], v[198:201], v[182:185], v[22:25]
	v_mfma_f32_16x16x32_bf16 v[18:21], v[206:209], v[182:185], v[18:21]
	v_mfma_f32_16x16x32_bf16 v[6:9], v[198:201], v[190:193], v[6:9]
	v_mfma_f32_16x16x32_bf16 v[2:5], v[206:209], v[190:193], v[2:5]
	v_mfma_f32_16x16x32_bf16 v[54:57], v[202:205], v[170:173], v[54:57]
	v_mfma_f32_16x16x32_bf16 v[50:53], v[210:213], v[170:173], v[50:53]
	v_mfma_f32_16x16x32_bf16 v[38:41], v[202:205], v[178:181], v[38:41]
	v_mfma_f32_16x16x32_bf16 v[34:37], v[210:213], v[178:181], v[34:37]
	v_mfma_f32_16x16x32_bf16 v[22:25], v[202:205], v[186:189], v[22:25]
	v_mfma_f32_16x16x32_bf16 v[18:21], v[210:213], v[186:189], v[18:21]
	v_mfma_f32_16x16x32_bf16 v[6:9], v[202:205], v[194:197], v[6:9]
	v_mfma_f32_16x16x32_bf16 v[2:5], v[210:213], v[194:197], v[2:5]
	v_or_b32_e32 v140, 0x18000, v146
	v_add_u32_e32 v148, 0x18400, v146
	v_add_u32_e32 v152, 0x18800, v146
	v_add_u32_e32 v156, 0x18c00, v146
	s_barrier
	ds_read_b128 v[140:143], v140
	ds_read_b128 v[148:151], v148
	ds_read_b128 v[152:155], v152
	ds_read_b128 v[156:159], v156
	s_add_u32 s24, s90, 0xb0000
	s_addc_u32 s25, s91, 0
	s_mov_b32 m0, s53
	v_lshl_add_u64 v[198:199], s[24:25], 0, v[130:131]
	ds_read_b128 v[166:169], v145 offset:32768
	ds_read_b128 v[170:173], v145 offset:33792
	ds_read_b128 v[174:177], v145 offset:34816
	ds_read_b128 v[178:181], v145 offset:35840
	ds_read_b128 v[182:185], v145 offset:36864
	ds_read_b128 v[186:189], v145 offset:37888
	ds_read_b128 v[190:193], v145 offset:38912
	ds_read_b128 v[194:197], v145 offset:39936
	global_load_lds_dwordx4 v[198:199], off
	v_lshl_add_u64 v[198:199], s[24:25], 0, v[132:133]
	s_mov_b32 m0, s58
	s_nop 0
	global_load_lds_dwordx4 v[198:199], off
	s_waitcnt lgkmcnt(8)
	s_barrier
	s_waitcnt lgkmcnt(0)
	s_waitcnt lgkmcnt(0)
	v_mfma_f32_16x16x32_bf16 v[126:129], v[140:143], v[166:169], v[126:129]
	v_mfma_f32_16x16x32_bf16 v[122:125], v[152:155], v[166:169], v[122:125]
	v_mfma_f32_16x16x32_bf16 v[110:113], v[140:143], v[174:177], v[110:113]
	v_mfma_f32_16x16x32_bf16 v[106:109], v[152:155], v[174:177], v[106:109]
	v_mfma_f32_16x16x32_bf16 v[94:97], v[140:143], v[182:185], v[94:97]
	v_mfma_f32_16x16x32_bf16 v[90:93], v[152:155], v[182:185], v[90:93]
	v_mfma_f32_16x16x32_bf16 v[78:81], v[140:143], v[190:193], v[78:81]
	v_mfma_f32_16x16x32_bf16 v[74:77], v[152:155], v[190:193], v[74:77]
	v_mfma_f32_16x16x32_bf16 v[126:129], v[148:151], v[170:173], v[126:129]
	v_mfma_f32_16x16x32_bf16 v[122:125], v[156:159], v[170:173], v[122:125]
	v_mfma_f32_16x16x32_bf16 v[110:113], v[148:151], v[178:181], v[110:113]
	v_mfma_f32_16x16x32_bf16 v[106:109], v[156:159], v[178:181], v[106:109]
	v_mfma_f32_16x16x32_bf16 v[94:97], v[148:151], v[186:189], v[94:97]
	v_mfma_f32_16x16x32_bf16 v[90:93], v[156:159], v[186:189], v[90:93]
	v_mfma_f32_16x16x32_bf16 v[78:81], v[148:151], v[194:197], v[78:81]
	v_mfma_f32_16x16x32_bf16 v[74:77], v[156:159], v[194:197], v[74:77]
	s_barrier
	v_or_b32_e32 v163, 0x1c000, v146
	s_mov_b32 m0, s59
	v_add_u32_e32 v165, 0x1c400, v146
	ds_read_b128 v[198:201], v163
	ds_read_b128 v[202:205], v165
	v_add_u32_e32 v163, 0x1c800, v146
	v_lshl_add_u64 v[160:161], v[160:161], 0, s[10:11]
	v_add_u32_e32 v165, 0x1cc00, v146
	ds_read_b128 v[206:209], v163
	ds_read_b128 v[210:213], v165
	global_load_lds_dwordx4 v[160:161], off
	v_lshl_add_u64 v[160:161], v[214:215], 0, s[10:11]
	s_mov_b32 m0, s60
	s_nop 0
	global_load_lds_dwordx4 v[160:161], off
	s_barrier
	s_waitcnt lgkmcnt(0)
	s_waitcnt lgkmcnt(0)
	v_mfma_f32_16x16x32_bf16 v[118:121], v[198:201], v[166:169], v[118:121]
	v_mfma_f32_16x16x32_bf16 v[114:117], v[206:209], v[166:169], v[114:117]
	v_mfma_f32_16x16x32_bf16 v[102:105], v[198:201], v[174:177], v[102:105]
	v_mfma_f32_16x16x32_bf16 v[98:101], v[206:209], v[174:177], v[98:101]
	v_mfma_f32_16x16x32_bf16 v[86:89], v[198:201], v[182:185], v[86:89]
	v_mfma_f32_16x16x32_bf16 v[82:85], v[206:209], v[182:185], v[82:85]
	v_mfma_f32_16x16x32_bf16 v[70:73], v[198:201], v[190:193], v[70:73]
	v_mfma_f32_16x16x32_bf16 v[66:69], v[206:209], v[190:193], v[66:69]
	v_mfma_f32_16x16x32_bf16 v[118:121], v[202:205], v[170:173], v[118:121]
	v_mfma_f32_16x16x32_bf16 v[114:117], v[210:213], v[170:173], v[114:117]
	v_mfma_f32_16x16x32_bf16 v[102:105], v[202:205], v[178:181], v[102:105]
	v_mfma_f32_16x16x32_bf16 v[98:101], v[210:213], v[178:181], v[98:101]
	v_mfma_f32_16x16x32_bf16 v[86:89], v[202:205], v[186:189], v[86:89]
	v_mfma_f32_16x16x32_bf16 v[82:85], v[210:213], v[186:189], v[82:85]
	v_mfma_f32_16x16x32_bf16 v[70:73], v[202:205], v[194:197], v[70:73]
	v_mfma_f32_16x16x32_bf16 v[66:69], v[210:213], v[194:197], v[66:69]
	s_mov_b32 m0, s62
	v_lshl_add_u64 v[160:161], v[216:217], 0, s[10:11]
	s_barrier
	ds_read_b128 v[166:169], v145 offset:49152
	ds_read_b128 v[170:173], v145 offset:50176
	ds_read_b128 v[174:177], v145 offset:51200
	ds_read_b128 v[178:181], v145 offset:52224
	ds_read_b128 v[182:185], v145 offset:53248
	ds_read_b128 v[186:189], v145 offset:54272
	ds_read_b128 v[190:193], v145 offset:55296
	ds_read_b128 v[194:197], v145 offset:56320
	global_load_lds_dwordx4 v[160:161], off
	v_lshl_add_u64 v[160:161], v[218:219], 0, s[10:11]
	s_mov_b32 m0, s72
	s_nop 0
	global_load_lds_dwordx4 v[160:161], off
	s_barrier
; DI bf16_t f2bf(float x) { unsigned u = __float_as_uint(x); u += 0x7fffu + ((u >> 16) & 1u); return (bf16_t)(u >> 16); }
; DI unsigned pack2(float lo, float hi) { f32x2_t v = {lo, hi}; return __builtin_bit_cast(unsigned, __builtin_convertvector(v, bf16x2_t)); }
; #define PG8_LAS __attribute__((address_space(3)))
; #define PG8_STAGE(bufoff, gbase, voff) do { _Pragma("unroll") for (int _i = 0; _i < 2; ++_i) \
;     __builtin_amdgcn_global_load_lds((const unsigned*)((const char*)(gbase) + (voff)[_i]), (PG8_LAS unsigned*)(lds + (bufoff) + ldsw + _i * 8192), 16, 0, 0); } while (0)
; #define PG8_MMA(ai, bj, At, Bt) do { __builtin_amdgcn_s_setprio(1); _Pragma("unroll") for (int m = 0; m < 4; ++m) _Pragma("unroll") for (int n = 0; n < 2; ++n) _Pragma("unroll") for (int k = 0; k < 2; ++k) \
;     acc[ai][bj][m][n] = __builtin_amdgcn_mfma_f32_16x16x32_bf16(Bt[n][k], At[m][k], acc[ai][bj][m][n], 0, 0, 0); __builtin_amdgcn_s_setprio(0); } while (0)
; #define PG8_BAR __builtin_amdgcn_s_barrier()
;   DI void operator()(const f32x4 (&acc)[2][2][4][2], const Unit& u, int wr, int wc, int fr, int fq, const PG8_LAS float*) const {
;     const int row0 = u.pm * BM + wr * 64 + fr, col0 = u.pn * BM + wc * 32 + 8 * fq;
; #pragma unroll
;     for (int ai = 0; ai < 2; ++ai)
; #pragma unroll
;       for (int m = 0; m < 4; ++m) { const int row = row0 + ai * HALF + m * 16; bf16_t* rowp = dst + (size_t)row * DM + col0; float ss = 0.f;
; #pragma unroll
;         for (int bj = 0; bj < 2; ++bj) { const f32x4 v0 = acc[ai][bj][m][0] * coef, v1 = acc[ai][bj][m][1] * coef;
;           ss += v0[0] * v0[0] + v0[1] * v0[1] + v0[2] * v0[2] + v0[3] * v0[3] + v1[0] * v1[0] + v1[1] * v1[1] + v1[2] * v1[2] + v1[3] * v1[3];
;           u32x4 w; w.x = pack2(v0[0], v0[1]); w.y = pack2(v0[2], v0[3]); w.z = pack2(v1[0], v1[1]); w.w = pack2(v1[2], v1[3]);
;           *(u32x4*)(rowp + bj * HALF) = w; }
;         ss += __shfl_xor(ss, 16); ss += __shfl_xor(ss, 32);
;         if (fq == 0) ssq[(size_t)row * 16 + u.pn * 4 + wc] = f2bf(ss); }
; template <class Epi>
; DI void gemm_phase(const bf16_t* __restrict__ gA, const bf16_t* __restrict__ gBt, int M, int N, int K, const Epi& E, char* lds_generic) {
;     ...
;       PG8_BAR; PG8_WAIT_L(0); PG8_MMA(1, 0, At, B0); PG8_BAR; PG8_SCHED;
;       PG8_STAGE(PG8_SB(1, 1), b3 + hstep, voffB);
;       PG8_WAIT_V(6); PG8_BAR; PG8_MMA(1, 1, At, B1); PG8_BAR;
	s_waitcnt lgkmcnt(0)
	s_waitcnt lgkmcnt(0)
	v_mfma_f32_16x16x32_bf16 v[62:65], v[140:143], v[166:169], v[62:65]
	v_mfma_f32_16x16x32_bf16 v[58:61], v[152:155], v[166:169], v[58:61]
	v_mfma_f32_16x16x32_bf16 v[46:49], v[140:143], v[174:177], v[46:49]
	v_mfma_f32_16x16x32_bf16 v[42:45], v[152:155], v[174:177], v[42:45]
	v_mfma_f32_16x16x32_bf16 v[30:33], v[140:143], v[182:185], v[30:33]
	v_mfma_f32_16x16x32_bf16 v[26:29], v[152:155], v[182:185], v[26:29]
	v_mfma_f32_16x16x32_bf16 v[14:17], v[140:143], v[190:193], v[14:17]
	v_mfma_f32_16x16x32_bf16 v[10:13], v[152:155], v[190:193], v[10:13]
	v_mfma_f32_16x16x32_bf16 v[62:65], v[148:151], v[170:173], v[62:65]
	v_mfma_f32_16x16x32_bf16 v[58:61], v[156:159], v[170:173], v[58:61]
	v_mfma_f32_16x16x32_bf16 v[46:49], v[148:151], v[178:181], v[46:49]
	v_mfma_f32_16x16x32_bf16 v[42:45], v[156:159], v[178:181], v[42:45]
	v_mfma_f32_16x16x32_bf16 v[30:33], v[148:151], v[186:189], v[30:33]
	v_mfma_f32_16x16x32_bf16 v[26:29], v[156:159], v[186:189], v[26:29]
	v_mfma_f32_16x16x32_bf16 v[14:17], v[148:151], v[194:197], v[14:17]
	v_mfma_f32_16x16x32_bf16 v[10:13], v[156:159], v[194:197], v[10:13]
	s_barrier
	s_add_u32 s24, s30, 0xb0080
	s_addc_u32 s25, s31, 0
	s_mov_b32 m0, s74
	v_lshl_add_u64 v[140:141], s[24:25], 0, v[0:1]
	global_load_lds_dwordx4 v[140:141], off
	v_lshl_add_u64 v[140:141], s[24:25], 0, v[134:135]
	s_mov_b32 m0, s19
	s_nop 0
	global_load_lds_dwordx4 v[140:141], off
	s_waitcnt vmcnt(6)
	s_barrier
	v_mfma_f32_16x16x32_bf16 v[54:57], v[198:201], v[166:169], v[54:57]
	v_mfma_f32_16x16x32_bf16 v[50:53], v[206:209], v[166:169], v[50:53]
	v_mfma_f32_16x16x32_bf16 v[38:41], v[198:201], v[174:177], v[38:41]
	v_mfma_f32_16x16x32_bf16 v[34:37], v[206:209], v[174:177], v[34:37]
	v_mfma_f32_16x16x32_bf16 v[22:25], v[198:201], v[182:185], v[22:25]
	v_mfma_f32_16x16x32_bf16 v[18:21], v[206:209], v[182:185], v[18:21]
	v_mfma_f32_16x16x32_bf16 v[6:9], v[198:201], v[190:193], v[6:9]
	v_mfma_f32_16x16x32_bf16 v[2:5], v[206:209], v[190:193], v[2:5]
	v_mfma_f32_16x16x32_bf16 v[54:57], v[202:205], v[170:173], v[54:57]
	v_mfma_f32_16x16x32_bf16 v[50:53], v[210:213], v[170:173], v[50:53]
	v_mfma_f32_16x16x32_bf16 v[38:41], v[202:205], v[178:181], v[38:41]
	v_mfma_f32_16x16x32_bf16 v[34:37], v[210:213], v[178:181], v[34:37]
	v_mfma_f32_16x16x32_bf16 v[22:25], v[202:205], v[186:189], v[22:25]
	v_mfma_f32_16x16x32_bf16 v[18:21], v[210:213], v[186:189], v[18:21]
	v_mfma_f32_16x16x32_bf16 v[6:9], v[202:205], v[194:197], v[6:9]
	v_mfma_f32_16x16x32_bf16 v[2:5], v[210:213], v[194:197], v[2:5]
	s_add_i32 s23, s23, 2
	s_add_u32 s21, s21, 0x100
	s_addc_u32 s22, s22, 0
	s_cmp_gt_u32 s23, 41
	s_mov_b64 s[88:89], s[28:29]
	s_barrier
	s_cbranch_scc0 .LBB0_684
	v_pk_mul_f32 v[126:127], v[126:127], 0.5 op_sel_hi:[1,0]
	v_pk_mul_f32 v[128:129], v[128:129], 0.5 op_sel_hi:[1,0]
	v_mul_f32_e32 v154, v127, v127
	v_fmac_f32_e32 v154, v126, v126
	v_fmac_f32_e32 v154, v128, v128
	v_pk_mul_f32 v[118:119], v[118:119], 0.5 op_sel_hi:[1,0]
	v_pk_mul_f32 v[152:153], v[124:125], 0.5 op_sel_hi:[1,0]
	v_pk_mul_f32 v[124:125], v[122:123], 0.5 op_sel_hi:[1,0]
	v_fmac_f32_e32 v154, v129, v129
	v_cvt_pk_bf16_f32 v123, v128, v129
	v_pk_mul_f32 v[128:129], v[114:115], 0.5 op_sel_hi:[1,0]
	v_mul_f32_e32 v114, v119, v119
	v_pk_mul_f32 v[120:121], v[120:121], 0.5 op_sel_hi:[1,0]
	v_fmac_f32_e32 v114, v118, v118
	v_fmac_f32_e32 v114, v120, v120
	v_fmac_f32_e32 v114, v121, v121
	v_fmac_f32_e32 v154, v124, v124
	v_fmac_f32_e32 v114, v128, v128
	v_xor_b32_e32 v143, 16, v223
	v_fmac_f32_e32 v154, v125, v125
	v_cvt_pk_bf16_f32 v122, v126, v127
	v_pk_mul_f32 v[126:127], v[116:117], 0.5 op_sel_hi:[1,0]
	v_fmac_f32_e32 v114, v129, v129
	v_cmp_lt_i32_e32 vcc, v143, v225
	v_fmac_f32_e32 v154, v152, v152
	v_fmac_f32_e32 v114, v126, v126
	v_cndmask_b32_e32 v143, v223, v143, vcc
	v_fmac_f32_e32 v154, v153, v153
	v_fmac_f32_e32 v114, v127, v127
	v_lshlrev_b32_e32 v149, 2, v143
	v_add_f32_e32 v114, v154, v114
	ds_bpermute_b32 v115, v149, v114
	v_xor_b32_e32 v143, 32, v223
	v_cmp_lt_i32_e32 vcc, v143, v225
	v_lshl_add_u32 v142, s9, 8, v144
	v_lshl_or_b32 v140, s76, 8, v147
	v_cndmask_b32_e32 v143, v223, v143, vcc
	v_lshlrev_b32_e32 v148, 2, v143
	s_waitcnt lgkmcnt(0)
	v_add_f32_e32 v114, v114, v115
	ds_bpermute_b32 v115, v148, v114
	v_ashrrev_i32_e32 v143, 31, v142
	v_lshlrev_b64 v[150:151], 11, v[142:143]
	v_ashrrev_i32_e32 v141, 31, v140
	s_lshl_b32 s28, s76, 2
	v_lshl_add_u64 v[150:151], s[26:27], 0, v[150:151]
	s_ashr_i32 s29, s28, 31
	v_lshl_add_u64 v[150:151], v[140:141], 1, v[150:151]
	v_cvt_pk_bf16_f32 v124, v124, v125
	v_cvt_pk_bf16_f32 v125, v152, v153
	v_cvt_pk_bf16_f32 v116, v118, v119
	v_cvt_pk_bf16_f32 v117, v120, v121
	v_cvt_pk_bf16_f32 v118, v128, v129
	v_cvt_pk_bf16_f32 v119, v126, v127
	global_store_dwordx4 v[150:151], v[122:125], off
	global_store_dwordx4 v[150:151], v[116:119], off offset:256
	s_and_saveexec_b64 s[30:31], s[36:37]
	s_cbranch_execz .LBB0_687
	s_waitcnt lgkmcnt(0)
	v_add_f32_e32 v114, v114, v115
	v_bfe_u32 v115, v114, 16, 1
	v_add3_u32 v116, v114, v115, s63
	v_lshlrev_b64 v[114:115], 5, v[142:143]
	v_lshl_add_u64 v[114:115], s[84:85], 0, v[114:115]
	v_lshl_add_u64 v[114:115], s[28:29], 1, v[114:115]
	s_lshl_b32 s76, s7, 1
	v_lshl_add_u64 v[114:115], v[114:115], 0, s[76:77]
	global_store_short_d16_hi v[114:115], v116, off
